# SwiGLU epilogue stores nt to sc1 write-through (all 4 FFN-in phases)
# baseline (speedup 1.0000x reference)
.LBB0_161:
	s_lshl_b32 s5, s12, 8
	v_mov_b32_e32 v82, v159
	v_mov_b32_e32 v83, v1
	s_add_i32 s5, s5, s31
	s_nop 0
	v_add_u32_e32 v182, s5, v82
	s_lshl_b32 s5, s42, 7
	s_or_b32 s5, s5, s34
	v_lshl_add_u32 v186, v83, 3, s5
	s_ashr_i32 s5, s12, 5
	s_mul_hi_i32 s7, s5, 0x5800
	s_mulk_i32 s5, 0x5800
	s_add_u32 s14, s28, s5
	s_addc_u32 s15, s29, s7
	v_ashrrev_i32_e32 v187, 31, v186
	v_lshl_add_u64 v[86:87], v[186:187], 2, s[14:15]
	s_mov_b64 s[14:15], 0x2c00
	s_movk_i32 s5, 0x2000
	global_load_dwordx4 v[82:85], v[86:87], off offset:16
	global_load_dwordx4 v[98:101], v[86:87], off
	v_lshl_add_u64 v[88:89], v[86:87], 0, s[14:15]
	v_add_co_u32_e32 v86, vcc, s5, v86
	v_ashrrev_i32_e32 v183, 31, v182
	s_nop 0
	v_addc_co_u32_e32 v87, vcc, 0, v87, vcc
	v_lshl_add_u64 v[160:161], v[182:183], 2, s[0:1]
	global_load_dwordx4 v[102:105], v[86:87], off offset:3072
	s_nop 0
	global_load_dwordx4 v[86:89], v[88:89], off offset:16
	v_add_u32_e32 v187, 16, v182
	global_load_dword v158, v[160:161], off
	v_add_u32_e32 v185, 32, v182
	v_add_u32_e32 v183, 48, v182
	v_add_u32_e32 v181, 0x80, v182
	v_add_u32_e32 v179, 0x90, v182
	v_add_u32_e32 v177, 0xa0, v182
	v_add_u32_e32 v175, 0xb0, v182
	s_waitcnt vmcnt(0)
	v_fmamk_f32 v158, v158, 0x3a800000, v223
	v_cmp_gt_f32_e32 vcc, s95, v158
	v_mul_f32_e32 v168, 0x4b800000, v158
	s_nop 0
	v_cndmask_b32_e32 v158, v158, v168, vcc
	v_rsq_f32_e32 v158, v158
	s_nop 0
	v_mul_f32_e32 v168, 0x45800000, v158
	v_cndmask_b32_e32 v184, v158, v168, vcc
	global_load_dword v158, v[160:161], off offset:64
	s_waitcnt vmcnt(0)
	v_fmamk_f32 v158, v158, 0x3a800000, v223
	v_cmp_gt_f32_e32 vcc, s95, v158
	v_mul_f32_e32 v168, 0x4b800000, v158
	s_nop 0
	v_cndmask_b32_e32 v158, v158, v168, vcc
	v_rsq_f32_e32 v158, v158
	s_nop 0
	v_mul_f32_e32 v168, 0x45800000, v158
	v_cndmask_b32_e32 v180, v158, v168, vcc
	global_load_dword v158, v[160:161], off offset:128
	s_waitcnt vmcnt(0)
	v_fmamk_f32 v158, v158, 0x3a800000, v223
	v_cmp_gt_f32_e32 vcc, s95, v158
	v_mul_f32_e32 v168, 0x4b800000, v158
	s_nop 0
	v_cndmask_b32_e32 v158, v158, v168, vcc
	v_rsq_f32_e32 v158, v158
	s_nop 0
	v_mul_f32_e32 v168, 0x45800000, v158
	v_cndmask_b32_e32 v178, v158, v168, vcc
	global_load_dword v158, v[160:161], off offset:192
	s_waitcnt vmcnt(0)
	v_fmamk_f32 v158, v158, 0x3a800000, v223
	v_cmp_gt_f32_e32 vcc, s95, v158
	v_mul_f32_e32 v168, 0x4b800000, v158
	s_nop 0
	v_cndmask_b32_e32 v158, v158, v168, vcc
	v_rsq_f32_e32 v158, v158
	s_nop 0
	v_mul_f32_e32 v168, 0x45800000, v158
	v_cndmask_b32_e32 v176, v158, v168, vcc
	global_load_dword v158, v[160:161], off offset:512
	s_waitcnt vmcnt(0)
	v_fmamk_f32 v158, v158, 0x3a800000, v223
	v_cmp_gt_f32_e32 vcc, s95, v158
	v_mul_f32_e32 v168, 0x4b800000, v158
	s_nop 0
	v_cndmask_b32_e32 v158, v158, v168, vcc
	v_rsq_f32_e32 v158, v158
	s_nop 0
	v_mul_f32_e32 v168, 0x45800000, v158
	v_cndmask_b32_e32 v174, v158, v168, vcc
	global_load_dword v158, v[160:161], off offset:576
	s_waitcnt vmcnt(0)
	v_fmamk_f32 v158, v158, 0x3a800000, v223
	v_cmp_gt_f32_e32 vcc, s95, v158
	v_mul_f32_e32 v168, 0x4b800000, v158
	s_nop 0
	v_cndmask_b32_e32 v158, v158, v168, vcc
	v_rsq_f32_e32 v158, v158
	s_nop 0
	v_mul_f32_e32 v168, 0x45800000, v158
	v_cndmask_b32_e32 v172, v158, v168, vcc
	global_load_dword v158, v[160:161], off offset:640
	s_waitcnt vmcnt(0)
	v_fmamk_f32 v158, v158, 0x3a800000, v223
	global_load_dword v160, v[160:161], off offset:704
	v_cmp_gt_f32_e32 vcc, s95, v158
	v_mul_f32_e32 v168, 0x4b800000, v158
	s_waitcnt vmcnt(0)
	v_fmamk_f32 v160, v160, 0x3a800000, v223
	v_cndmask_b32_e32 v158, v158, v168, vcc
	v_rsq_f32_e32 v158, v158
	v_mul_f32_e32 v161, 0x4b800000, v160
	v_mul_f32_e32 v168, 0x45800000, v158
	v_cndmask_b32_e32 v158, v158, v168, vcc
	v_cmp_gt_f32_e32 vcc, s95, v160
	s_nop 1
	v_cndmask_b32_e32 v160, v160, v161, vcc
	v_rsq_f32_e32 v160, v160
	s_nop 0
	v_mul_f32_e32 v161, 0x45800000, v160
	v_cndmask_b32_e32 v160, v160, v161, vcc
	v_ashrrev_i32_e32 v161, 6, v186
	v_and_b32_e32 v186, 56, v186
	v_pk_fma_f32 v[138:139], v[138:139], v[184:185], v[98:99] op_sel_hi:[1,0,1]
	v_pk_fma_f32 v[142:143], v[142:143], v[184:185], v[102:103] op_sel_hi:[1,0,1]
	v_mul_f32_e32 v168, 0xbfb8aa3b, v138
	v_mul_f32_e32 v169, 0xbfb8aa3b, v139
	v_exp_f32_e32 v168, v168
	v_exp_f32_e32 v169, v169
	v_pk_fma_f32 v[140:141], v[140:141], v[184:185], v[100:101] op_sel_hi:[1,0,1]
	v_pk_fma_f32 v[134:135], v[134:135], v[184:185], v[82:83] op_sel_hi:[1,0,1]
	v_add_f32_e32 v168, 1.0, v168
	v_add_f32_e32 v169, 1.0, v169
	v_rcp_f32_e32 v168, v168
	v_rcp_f32_e32 v169, v169
	v_pk_fma_f32 v[130:131], v[130:131], v[184:185], v[86:87] op_sel_hi:[1,0,1]
	v_pk_fma_f32 v[132:133], v[132:133], v[184:185], v[88:89] op_sel_hi:[1,0,1]
	v_readlane_b32 s14, v254, 27
	v_pk_mul_f32 v[138:139], v[138:139], v[168:169]
	v_readlane_b32 s15, v254, 28
	v_pk_mul_f32 v[138:139], v[142:143], v[138:139]
	v_pk_fma_f32 v[142:143], v[144:145], v[184:185], v[104:105] op_sel_hi:[1,0,1]
	v_mul_f32_e32 v144, 0xbfb8aa3b, v140
	v_mul_f32_e32 v145, 0xbfb8aa3b, v141
	v_exp_f32_e32 v144, v144
	v_exp_f32_e32 v145, v145
	v_add_f32_e32 v144, 1.0, v144
	v_add_f32_e32 v145, 1.0, v145
	v_rcp_f32_e32 v144, v144
	v_rcp_f32_e32 v145, v145
	s_nop 0
	v_pk_mul_f32 v[140:141], v[140:141], v[144:145]
	s_nop 0
	v_pk_mul_f32 v[140:141], v[142:143], v[140:141]
	v_mul_f32_e32 v142, 0xbfb8aa3b, v134
	v_mul_f32_e32 v143, 0xbfb8aa3b, v135
	v_exp_f32_e32 v142, v142
	v_exp_f32_e32 v143, v143
	v_add_f32_e32 v142, 1.0, v142
	v_add_f32_e32 v143, 1.0, v143
	v_rcp_f32_e32 v142, v142
	v_rcp_f32_e32 v143, v143
	s_nop 0
	v_pk_mul_f32 v[134:135], v[134:135], v[142:143]
	s_nop 0
	v_pk_mul_f32 v[130:131], v[130:131], v[134:135]
	v_pk_fma_f32 v[134:135], v[136:137], v[184:185], v[84:85] op_sel_hi:[1,0,1]
	s_nop 0
	v_mul_f32_e32 v136, 0xbfb8aa3b, v134
	v_mul_f32_e32 v137, 0xbfb8aa3b, v135
	v_exp_f32_e32 v136, v136
	v_exp_f32_e32 v137, v137
	v_add_f32_e32 v136, 1.0, v136
	v_add_f32_e32 v137, 1.0, v137
	v_rcp_f32_e32 v136, v136
	v_rcp_f32_e32 v137, v137
	s_nop 0
	v_pk_mul_f32 v[134:135], v[134:135], v[136:137]
	s_nop 0
	v_pk_mul_f32 v[136:137], v[132:133], v[134:135]
	v_cvt_pk_bf16_f32 v134, v130, v131
	v_lshrrev_b32_e32 v130, 8, v182
	v_mad_i32_i24 v130, v130, 44, v161
	v_ashrrev_i32_e32 v131, 31, v130
	v_cvt_pk_bf16_f32 v135, v136, v137
	v_lshlrev_b64 v[130:131], 15, v[130:131]
	v_lshlrev_b32_e32 v136, 7, v182
	v_lshl_add_u64 v[130:131], s[14:15], 0, v[130:131]
	v_and_b32_e32 v136, 0x7f80, v136
	v_mov_b32_e32 v137, v0
	v_lshl_add_u64 v[136:137], v[130:131], 0, v[136:137]
	v_lshlrev_b32_e32 v130, 1, v186
	v_mov_b32_e32 v131, v0
	v_cvt_pk_bf16_f32 v132, v138, v139
	v_cvt_pk_bf16_f32 v133, v140, v141
	v_lshl_add_u64 v[136:137], v[136:137], 0, v[130:131]
	global_store_dwordx4 v[136:137], v[132:135], off sc1
	v_pk_fma_f32 v[126:127], v[126:127], v[180:181], v[98:99] op_sel_hi:[1,0,1]
	v_pk_fma_f32 v[122:123], v[122:123], v[180:181], v[102:103] op_sel_hi:[1,0,1]
	v_mul_f32_e32 v132, 0xbfb8aa3b, v126
	v_mul_f32_e32 v133, 0xbfb8aa3b, v127
	v_exp_f32_e32 v132, v132
	v_exp_f32_e32 v133, v133
	v_pk_fma_f32 v[124:125], v[124:125], v[180:181], v[104:105] op_sel_hi:[1,0,1]
	v_pk_fma_f32 v[118:119], v[118:119], v[180:181], v[82:83] op_sel_hi:[1,0,1]
	v_add_f32_e32 v132, 1.0, v132
	v_add_f32_e32 v133, 1.0, v133
	v_rcp_f32_e32 v132, v132
	v_rcp_f32_e32 v133, v133
	v_pk_fma_f32 v[114:115], v[114:115], v[180:181], v[86:87] op_sel_hi:[1,0,1]
	v_pk_fma_f32 v[116:117], v[116:117], v[180:181], v[88:89] op_sel_hi:[1,0,1]
	v_pk_mul_f32 v[126:127], v[126:127], v[132:133]
	s_nop 0
	v_pk_mul_f32 v[122:123], v[122:123], v[126:127]
	v_pk_fma_f32 v[126:127], v[128:129], v[180:181], v[100:101] op_sel_hi:[1,0,1]
	s_nop 0
	v_mul_f32_e32 v128, 0xbfb8aa3b, v126
	v_mul_f32_e32 v129, 0xbfb8aa3b, v127
	v_exp_f32_e32 v128, v128
	v_exp_f32_e32 v129, v129
	v_add_f32_e32 v128, 1.0, v128
	v_add_f32_e32 v129, 1.0, v129
	v_rcp_f32_e32 v128, v128
	v_rcp_f32_e32 v129, v129
	s_nop 0
	v_pk_mul_f32 v[126:127], v[126:127], v[128:129]
	s_nop 0
	v_pk_mul_f32 v[124:125], v[124:125], v[126:127]
	v_mul_f32_e32 v126, 0xbfb8aa3b, v118
	v_mul_f32_e32 v127, 0xbfb8aa3b, v119
	v_exp_f32_e32 v126, v126
	v_exp_f32_e32 v127, v127
	v_add_f32_e32 v126, 1.0, v126
	v_add_f32_e32 v127, 1.0, v127
	v_rcp_f32_e32 v126, v126
	v_rcp_f32_e32 v127, v127
	s_nop 0
	v_pk_mul_f32 v[118:119], v[118:119], v[126:127]
	s_nop 0
	v_pk_mul_f32 v[118:119], v[114:115], v[118:119]
	v_pk_fma_f32 v[114:115], v[120:121], v[180:181], v[84:85] op_sel_hi:[1,0,1]
	s_nop 0
	v_mul_f32_e32 v120, 0xbfb8aa3b, v114
	v_mul_f32_e32 v121, 0xbfb8aa3b, v115
	v_exp_f32_e32 v120, v120
	v_exp_f32_e32 v121, v121
	v_add_f32_e32 v120, 1.0, v120
	v_add_f32_e32 v121, 1.0, v121
	v_rcp_f32_e32 v120, v120
	v_rcp_f32_e32 v121, v121
	s_nop 0
	v_pk_mul_f32 v[114:115], v[114:115], v[120:121]
	s_nop 0
	v_pk_mul_f32 v[120:121], v[116:117], v[114:115]
	v_cvt_pk_bf16_f32 v116, v118, v119
	v_lshrrev_b32_e32 v118, 8, v187
	v_mad_i32_i24 v118, v118, 44, v161
	v_ashrrev_i32_e32 v119, 31, v118
	v_cvt_pk_bf16_f32 v117, v120, v121
	v_lshlrev_b64 v[118:119], 15, v[118:119]
	v_lshlrev_b32_e32 v120, 7, v187
	v_lshl_add_u64 v[118:119], s[14:15], 0, v[118:119]
	v_and_b32_e32 v120, 0x7f80, v120
	v_mov_b32_e32 v121, v0
	v_lshl_add_u64 v[118:119], v[118:119], 0, v[120:121]
	v_cvt_pk_bf16_f32 v114, v122, v123
	v_cvt_pk_bf16_f32 v115, v124, v125
	v_lshl_add_u64 v[118:119], v[118:119], 0, v[130:131]
	global_store_dwordx4 v[118:119], v[114:117], off sc1
	v_pk_fma_f32 v[110:111], v[110:111], v[178:179], v[98:99] op_sel_hi:[1,0,1]
	v_pk_fma_f32 v[106:107], v[106:107], v[178:179], v[102:103] op_sel_hi:[1,0,1]
	v_mul_f32_e32 v114, 0xbfb8aa3b, v110
	v_mul_f32_e32 v115, 0xbfb8aa3b, v111
	v_exp_f32_e32 v114, v114
	v_exp_f32_e32 v115, v115
	v_pk_fma_f32 v[108:109], v[108:109], v[178:179], v[104:105] op_sel_hi:[1,0,1]
	v_pk_fma_f32 v[94:95], v[94:95], v[178:179], v[82:83] op_sel_hi:[1,0,1]
	v_add_f32_e32 v114, 1.0, v114
	v_add_f32_e32 v115, 1.0, v115
	v_rcp_f32_e32 v114, v114
	v_rcp_f32_e32 v115, v115
	v_pk_fma_f32 v[90:91], v[90:91], v[178:179], v[86:87] op_sel_hi:[1,0,1]
	v_pk_fma_f32 v[92:93], v[92:93], v[178:179], v[88:89] op_sel_hi:[1,0,1]
	v_pk_mul_f32 v[110:111], v[110:111], v[114:115]
	s_nop 0
	v_pk_mul_f32 v[106:107], v[106:107], v[110:111]
	v_pk_fma_f32 v[110:111], v[112:113], v[178:179], v[100:101] op_sel_hi:[1,0,1]
	s_nop 0
	v_mul_f32_e32 v112, 0xbfb8aa3b, v110
	v_mul_f32_e32 v113, 0xbfb8aa3b, v111
	v_exp_f32_e32 v112, v112
	v_exp_f32_e32 v113, v113
	v_add_f32_e32 v112, 1.0, v112
	v_add_f32_e32 v113, 1.0, v113
	v_rcp_f32_e32 v112, v112
	v_rcp_f32_e32 v113, v113
	s_nop 0
	v_pk_mul_f32 v[110:111], v[110:111], v[112:113]
	s_nop 0
	v_pk_mul_f32 v[108:109], v[108:109], v[110:111]
	v_mul_f32_e32 v110, 0xbfb8aa3b, v94
	v_mul_f32_e32 v111, 0xbfb8aa3b, v95
	v_exp_f32_e32 v110, v110
	v_exp_f32_e32 v111, v111
	v_add_f32_e32 v110, 1.0, v110
	v_add_f32_e32 v111, 1.0, v111
	v_rcp_f32_e32 v110, v110
	v_rcp_f32_e32 v111, v111
	s_nop 0
	v_pk_mul_f32 v[94:95], v[94:95], v[110:111]
	s_nop 0
	v_pk_mul_f32 v[94:95], v[90:91], v[94:95]
	v_pk_fma_f32 v[90:91], v[96:97], v[178:179], v[84:85] op_sel_hi:[1,0,1]
	s_nop 0
	v_mul_f32_e32 v96, 0xbfb8aa3b, v90
	v_mul_f32_e32 v97, 0xbfb8aa3b, v91
	v_exp_f32_e32 v96, v96
	v_exp_f32_e32 v97, v97
	v_add_f32_e32 v96, 1.0, v96
	v_add_f32_e32 v97, 1.0, v97
	v_rcp_f32_e32 v96, v96
	v_rcp_f32_e32 v97, v97
	s_nop 0
	v_pk_mul_f32 v[90:91], v[90:91], v[96:97]
	s_nop 0
	v_pk_mul_f32 v[96:97], v[92:93], v[90:91]
	v_cvt_pk_bf16_f32 v92, v94, v95
	v_lshrrev_b32_e32 v94, 8, v185
	v_mad_i32_i24 v94, v94, 44, v161
	v_ashrrev_i32_e32 v95, 31, v94
	v_cvt_pk_bf16_f32 v93, v96, v97
	v_lshlrev_b64 v[94:95], 15, v[94:95]
	v_lshlrev_b32_e32 v96, 7, v185
	v_lshl_add_u64 v[94:95], s[14:15], 0, v[94:95]
	v_and_b32_e32 v96, 0x7f80, v96
	v_mov_b32_e32 v97, v0
	v_lshl_add_u64 v[94:95], v[94:95], 0, v[96:97]
	v_cvt_pk_bf16_f32 v90, v106, v107
	v_cvt_pk_bf16_f32 v91, v108, v109
	v_lshl_add_u64 v[94:95], v[94:95], 0, v[130:131]
	global_store_dwordx4 v[94:95], v[90:93], off sc1
	v_pk_fma_f32 v[78:79], v[78:79], v[176:177], v[98:99] op_sel_hi:[1,0,1]
	v_pk_fma_f32 v[74:75], v[74:75], v[176:177], v[102:103] op_sel_hi:[1,0,1]
	v_mul_f32_e32 v90, 0xbfb8aa3b, v78
	v_mul_f32_e32 v91, 0xbfb8aa3b, v79
	v_exp_f32_e32 v90, v90
	v_exp_f32_e32 v91, v91
	v_pk_fma_f32 v[76:77], v[76:77], v[176:177], v[104:105] op_sel_hi:[1,0,1]
	v_pk_fma_f32 v[70:71], v[70:71], v[176:177], v[82:83] op_sel_hi:[1,0,1]
	v_add_f32_e32 v90, 1.0, v90
	v_add_f32_e32 v91, 1.0, v91
	v_rcp_f32_e32 v90, v90
	v_rcp_f32_e32 v91, v91
	v_pk_fma_f32 v[66:67], v[66:67], v[176:177], v[86:87] op_sel_hi:[1,0,1]
	v_pk_fma_f32 v[68:69], v[68:69], v[176:177], v[88:89] op_sel_hi:[1,0,1]
	v_pk_mul_f32 v[78:79], v[78:79], v[90:91]
	s_nop 0
	v_pk_mul_f32 v[74:75], v[74:75], v[78:79]
	v_pk_fma_f32 v[78:79], v[80:81], v[176:177], v[100:101] op_sel_hi:[1,0,1]
	s_nop 0
	v_mul_f32_e32 v80, 0xbfb8aa3b, v78
	v_mul_f32_e32 v81, 0xbfb8aa3b, v79
	v_exp_f32_e32 v80, v80
	v_exp_f32_e32 v81, v81
	v_add_f32_e32 v80, 1.0, v80
	v_add_f32_e32 v81, 1.0, v81
	v_rcp_f32_e32 v80, v80
	v_rcp_f32_e32 v81, v81
	s_nop 0
	v_pk_mul_f32 v[78:79], v[78:79], v[80:81]
	s_nop 0
	v_pk_mul_f32 v[76:77], v[76:77], v[78:79]
	v_mul_f32_e32 v78, 0xbfb8aa3b, v70
	v_mul_f32_e32 v79, 0xbfb8aa3b, v71
	v_exp_f32_e32 v78, v78
	v_exp_f32_e32 v79, v79
	v_add_f32_e32 v78, 1.0, v78
	v_add_f32_e32 v79, 1.0, v79
	v_rcp_f32_e32 v78, v78
	v_rcp_f32_e32 v79, v79
	s_nop 0
	v_pk_mul_f32 v[70:71], v[70:71], v[78:79]
	s_nop 0
	v_pk_mul_f32 v[70:71], v[66:67], v[70:71]
	v_pk_fma_f32 v[66:67], v[72:73], v[176:177], v[84:85] op_sel_hi:[1,0,1]
	s_nop 0
	v_mul_f32_e32 v72, 0xbfb8aa3b, v66
	v_mul_f32_e32 v73, 0xbfb8aa3b, v67
	v_exp_f32_e32 v72, v72
	v_exp_f32_e32 v73, v73
	v_add_f32_e32 v72, 1.0, v72
	v_add_f32_e32 v73, 1.0, v73
	v_rcp_f32_e32 v72, v72
	v_rcp_f32_e32 v73, v73
	s_nop 0
	v_pk_mul_f32 v[66:67], v[66:67], v[72:73]
	s_nop 0
	v_pk_mul_f32 v[72:73], v[68:69], v[66:67]
	v_cvt_pk_bf16_f32 v68, v70, v71
	v_lshrrev_b32_e32 v70, 8, v183
	v_mad_i32_i24 v70, v70, 44, v161
	v_ashrrev_i32_e32 v71, 31, v70
	v_cvt_pk_bf16_f32 v69, v72, v73
	v_lshlrev_b64 v[70:71], 15, v[70:71]
	v_lshlrev_b32_e32 v72, 7, v183
	v_lshl_add_u64 v[70:71], s[14:15], 0, v[70:71]
	v_and_b32_e32 v72, 0x7f80, v72
	v_mov_b32_e32 v73, v0
	v_lshl_add_u64 v[70:71], v[70:71], 0, v[72:73]
	v_cvt_pk_bf16_f32 v66, v74, v75
	v_cvt_pk_bf16_f32 v67, v76, v77
	v_lshl_add_u64 v[70:71], v[70:71], 0, v[130:131]
	global_store_dwordx4 v[70:71], v[66:69], off sc1
	v_pk_fma_f32 v[62:63], v[62:63], v[174:175], v[98:99] op_sel_hi:[1,0,1]
	v_pk_fma_f32 v[58:59], v[58:59], v[174:175], v[102:103] op_sel_hi:[1,0,1]
	v_mul_f32_e32 v66, 0xbfb8aa3b, v62
	v_mul_f32_e32 v67, 0xbfb8aa3b, v63
	v_exp_f32_e32 v66, v66
	v_exp_f32_e32 v67, v67
	v_pk_fma_f32 v[60:61], v[60:61], v[174:175], v[104:105] op_sel_hi:[1,0,1]
	v_pk_fma_f32 v[54:55], v[54:55], v[174:175], v[82:83] op_sel_hi:[1,0,1]
	v_add_f32_e32 v66, 1.0, v66
	v_add_f32_e32 v67, 1.0, v67
	v_rcp_f32_e32 v66, v66
	v_rcp_f32_e32 v67, v67
	v_pk_fma_f32 v[50:51], v[50:51], v[174:175], v[86:87] op_sel_hi:[1,0,1]
	v_pk_fma_f32 v[52:53], v[52:53], v[174:175], v[88:89] op_sel_hi:[1,0,1]
	v_pk_mul_f32 v[62:63], v[62:63], v[66:67]
	s_nop 0
	v_pk_mul_f32 v[58:59], v[58:59], v[62:63]
	v_pk_fma_f32 v[62:63], v[64:65], v[174:175], v[100:101] op_sel_hi:[1,0,1]
	s_nop 0
	v_mul_f32_e32 v64, 0xbfb8aa3b, v62
	v_mul_f32_e32 v65, 0xbfb8aa3b, v63
	v_exp_f32_e32 v64, v64
	v_exp_f32_e32 v65, v65
	v_add_f32_e32 v64, 1.0, v64
	v_add_f32_e32 v65, 1.0, v65
	v_rcp_f32_e32 v64, v64
	v_rcp_f32_e32 v65, v65
	s_nop 0
	v_pk_mul_f32 v[62:63], v[62:63], v[64:65]
	s_nop 0
	v_pk_mul_f32 v[60:61], v[60:61], v[62:63]
	v_mul_f32_e32 v62, 0xbfb8aa3b, v54
	v_mul_f32_e32 v63, 0xbfb8aa3b, v55
	v_exp_f32_e32 v62, v62
	v_exp_f32_e32 v63, v63
	v_add_f32_e32 v62, 1.0, v62
	v_add_f32_e32 v63, 1.0, v63
	v_rcp_f32_e32 v62, v62
	v_rcp_f32_e32 v63, v63
	s_nop 0
	v_pk_mul_f32 v[54:55], v[54:55], v[62:63]
	s_nop 0
	v_pk_mul_f32 v[54:55], v[50:51], v[54:55]
	v_pk_fma_f32 v[50:51], v[56:57], v[174:175], v[84:85] op_sel_hi:[1,0,1]
	s_nop 0
	v_mul_f32_e32 v56, 0xbfb8aa3b, v50
	v_mul_f32_e32 v57, 0xbfb8aa3b, v51
	v_exp_f32_e32 v56, v56
	v_exp_f32_e32 v57, v57
	v_add_f32_e32 v56, 1.0, v56
	v_add_f32_e32 v57, 1.0, v57
	v_rcp_f32_e32 v56, v56
	v_rcp_f32_e32 v57, v57
	s_nop 0
	v_pk_mul_f32 v[50:51], v[50:51], v[56:57]
	s_nop 0
	v_pk_mul_f32 v[56:57], v[52:53], v[50:51]
	v_cvt_pk_bf16_f32 v52, v54, v55
	v_lshrrev_b32_e32 v54, 8, v181
	v_mad_i32_i24 v54, v54, 44, v161
	v_ashrrev_i32_e32 v55, 31, v54
	v_cvt_pk_bf16_f32 v53, v56, v57
	v_lshlrev_b64 v[54:55], 15, v[54:55]
	v_lshlrev_b32_e32 v56, 7, v181
	v_lshl_add_u64 v[54:55], s[14:15], 0, v[54:55]
	v_and_b32_e32 v56, 0x7f80, v56
	v_mov_b32_e32 v57, v0
	v_lshl_add_u64 v[54:55], v[54:55], 0, v[56:57]
	v_cvt_pk_bf16_f32 v50, v58, v59
	v_cvt_pk_bf16_f32 v51, v60, v61
	v_lshl_add_u64 v[54:55], v[54:55], 0, v[130:131]
	global_store_dwordx4 v[54:55], v[50:53], off sc1
	v_pk_fma_f32 v[46:47], v[46:47], v[172:173], v[98:99] op_sel_hi:[1,0,1]
	v_pk_fma_f32 v[42:43], v[42:43], v[172:173], v[102:103] op_sel_hi:[1,0,1]
	v_mul_f32_e32 v50, 0xbfb8aa3b, v46
	v_mul_f32_e32 v51, 0xbfb8aa3b, v47
	v_exp_f32_e32 v50, v50
	v_exp_f32_e32 v51, v51
	v_pk_fma_f32 v[44:45], v[44:45], v[172:173], v[104:105] op_sel_hi:[1,0,1]
	v_pk_fma_f32 v[38:39], v[38:39], v[172:173], v[82:83] op_sel_hi:[1,0,1]
	v_add_f32_e32 v50, 1.0, v50
	v_add_f32_e32 v51, 1.0, v51
	v_rcp_f32_e32 v50, v50
	v_rcp_f32_e32 v51, v51
	v_pk_fma_f32 v[34:35], v[34:35], v[172:173], v[86:87] op_sel_hi:[1,0,1]
	v_pk_fma_f32 v[36:37], v[36:37], v[172:173], v[88:89] op_sel_hi:[1,0,1]
	v_pk_mul_f32 v[46:47], v[46:47], v[50:51]
	s_nop 0
	v_pk_mul_f32 v[42:43], v[42:43], v[46:47]
	v_pk_fma_f32 v[46:47], v[48:49], v[172:173], v[100:101] op_sel_hi:[1,0,1]
	s_nop 0
	v_mul_f32_e32 v48, 0xbfb8aa3b, v46
	v_mul_f32_e32 v49, 0xbfb8aa3b, v47
	v_exp_f32_e32 v48, v48
	v_exp_f32_e32 v49, v49
	v_add_f32_e32 v48, 1.0, v48
	v_add_f32_e32 v49, 1.0, v49
	v_rcp_f32_e32 v48, v48
	v_rcp_f32_e32 v49, v49
	s_nop 0
	v_pk_mul_f32 v[46:47], v[46:47], v[48:49]
	s_nop 0
	v_pk_mul_f32 v[44:45], v[44:45], v[46:47]
	v_mul_f32_e32 v46, 0xbfb8aa3b, v38
	v_mul_f32_e32 v47, 0xbfb8aa3b, v39
	v_exp_f32_e32 v46, v46
	v_exp_f32_e32 v47, v47
	v_add_f32_e32 v46, 1.0, v46
	v_add_f32_e32 v47, 1.0, v47
	v_rcp_f32_e32 v46, v46
	v_rcp_f32_e32 v47, v47
	s_nop 0
	v_pk_mul_f32 v[38:39], v[38:39], v[46:47]
	s_nop 0
	v_pk_mul_f32 v[38:39], v[34:35], v[38:39]
	v_pk_fma_f32 v[34:35], v[40:41], v[172:173], v[84:85] op_sel_hi:[1,0,1]
	s_nop 0
	v_mul_f32_e32 v40, 0xbfb8aa3b, v34
	v_mul_f32_e32 v41, 0xbfb8aa3b, v35
	v_exp_f32_e32 v40, v40
	v_exp_f32_e32 v41, v41
	v_add_f32_e32 v40, 1.0, v40
	v_add_f32_e32 v41, 1.0, v41
	v_rcp_f32_e32 v40, v40
	v_rcp_f32_e32 v41, v41
	s_nop 0
	v_pk_mul_f32 v[34:35], v[34:35], v[40:41]
	s_nop 0
	v_pk_mul_f32 v[40:41], v[36:37], v[34:35]
	v_cvt_pk_bf16_f32 v36, v38, v39
	v_lshrrev_b32_e32 v38, 8, v179
	v_mad_i32_i24 v38, v38, 44, v161
	v_ashrrev_i32_e32 v39, 31, v38
	v_cvt_pk_bf16_f32 v37, v40, v41
	v_lshlrev_b64 v[38:39], 15, v[38:39]
	v_lshlrev_b32_e32 v40, 7, v179
	v_lshl_add_u64 v[38:39], s[14:15], 0, v[38:39]
	v_and_b32_e32 v40, 0x7f80, v40
	v_mov_b32_e32 v41, v0
	v_lshl_add_u64 v[38:39], v[38:39], 0, v[40:41]
	v_cvt_pk_bf16_f32 v34, v42, v43
	v_cvt_pk_bf16_f32 v35, v44, v45
	v_lshl_add_u64 v[38:39], v[38:39], 0, v[130:131]
	global_store_dwordx4 v[38:39], v[34:37], off sc1
	v_pk_fma_f32 v[30:31], v[30:31], v[158:159], v[98:99] op_sel_hi:[1,0,1]
	v_pk_fma_f32 v[26:27], v[26:27], v[158:159], v[102:103] op_sel_hi:[1,0,1]
	v_mul_f32_e32 v34, 0xbfb8aa3b, v30
	v_mul_f32_e32 v35, 0xbfb8aa3b, v31
	v_exp_f32_e32 v34, v34
	v_exp_f32_e32 v35, v35
	v_pk_fma_f32 v[28:29], v[28:29], v[158:159], v[104:105] op_sel_hi:[1,0,1]
	v_pk_fma_f32 v[22:23], v[22:23], v[158:159], v[82:83] op_sel_hi:[1,0,1]
	v_add_f32_e32 v34, 1.0, v34
	v_add_f32_e32 v35, 1.0, v35
	v_rcp_f32_e32 v34, v34
	v_rcp_f32_e32 v35, v35
	v_pk_fma_f32 v[18:19], v[18:19], v[158:159], v[86:87] op_sel_hi:[1,0,1]
	v_pk_fma_f32 v[20:21], v[20:21], v[158:159], v[88:89] op_sel_hi:[1,0,1]
	v_pk_mul_f32 v[30:31], v[30:31], v[34:35]
	s_nop 0
	v_pk_mul_f32 v[26:27], v[26:27], v[30:31]
	v_pk_fma_f32 v[30:31], v[32:33], v[158:159], v[100:101] op_sel_hi:[1,0,1]
	s_nop 0
	v_mul_f32_e32 v32, 0xbfb8aa3b, v30
	v_mul_f32_e32 v33, 0xbfb8aa3b, v31
	v_exp_f32_e32 v32, v32
	v_exp_f32_e32 v33, v33
	v_add_f32_e32 v32, 1.0, v32
	v_add_f32_e32 v33, 1.0, v33
	v_rcp_f32_e32 v32, v32
	v_rcp_f32_e32 v33, v33
	s_nop 0
	v_pk_mul_f32 v[30:31], v[30:31], v[32:33]
	s_nop 0
	v_pk_mul_f32 v[28:29], v[28:29], v[30:31]
	v_mul_f32_e32 v30, 0xbfb8aa3b, v22
	v_mul_f32_e32 v31, 0xbfb8aa3b, v23
	v_exp_f32_e32 v30, v30
	v_exp_f32_e32 v31, v31
	v_add_f32_e32 v30, 1.0, v30
	v_add_f32_e32 v31, 1.0, v31
	v_rcp_f32_e32 v30, v30
	v_rcp_f32_e32 v31, v31
	s_nop 0
	v_pk_mul_f32 v[22:23], v[22:23], v[30:31]
	s_nop 0
	v_pk_mul_f32 v[22:23], v[18:19], v[22:23]
	v_pk_fma_f32 v[18:19], v[24:25], v[158:159], v[84:85] op_sel_hi:[1,0,1]
	s_nop 0
	v_mul_f32_e32 v24, 0xbfb8aa3b, v18
	v_mul_f32_e32 v25, 0xbfb8aa3b, v19
	v_exp_f32_e32 v24, v24
	v_exp_f32_e32 v25, v25
	v_add_f32_e32 v24, 1.0, v24
	v_add_f32_e32 v25, 1.0, v25
	v_rcp_f32_e32 v24, v24
	v_rcp_f32_e32 v25, v25
	s_nop 0
	v_pk_mul_f32 v[18:19], v[18:19], v[24:25]
	s_nop 0
	v_pk_mul_f32 v[24:25], v[20:21], v[18:19]
	v_cvt_pk_bf16_f32 v20, v22, v23
	v_lshrrev_b32_e32 v22, 8, v177
	v_mad_i32_i24 v22, v22, 44, v161
	v_ashrrev_i32_e32 v23, 31, v22
	v_cvt_pk_bf16_f32 v21, v24, v25
	v_lshlrev_b64 v[22:23], 15, v[22:23]
	v_lshlrev_b32_e32 v24, 7, v177
	v_lshl_add_u64 v[22:23], s[14:15], 0, v[22:23]
	v_and_b32_e32 v24, 0x7f80, v24
	v_mov_b32_e32 v25, v0
	v_lshl_add_u64 v[22:23], v[22:23], 0, v[24:25]
	v_cvt_pk_bf16_f32 v18, v26, v27
	v_cvt_pk_bf16_f32 v19, v28, v29
	v_lshl_add_u64 v[22:23], v[22:23], 0, v[130:131]
	global_store_dwordx4 v[22:23], v[18:21], off sc1
	v_pk_fma_f32 v[14:15], v[14:15], v[160:161], v[98:99] op_sel_hi:[1,0,1]
	v_pk_fma_f32 v[10:11], v[10:11], v[160:161], v[102:103] op_sel_hi:[1,0,1]
	v_mul_f32_e32 v18, 0xbfb8aa3b, v14
	v_mul_f32_e32 v19, 0xbfb8aa3b, v15
	v_exp_f32_e32 v18, v18
	v_exp_f32_e32 v19, v19
	v_pk_fma_f32 v[12:13], v[12:13], v[160:161], v[104:105] op_sel_hi:[1,0,1]
	v_pk_fma_f32 v[6:7], v[6:7], v[160:161], v[82:83] op_sel_hi:[1,0,1]
	v_add_f32_e32 v18, 1.0, v18
	v_add_f32_e32 v19, 1.0, v19
	v_rcp_f32_e32 v18, v18
	v_rcp_f32_e32 v19, v19
	v_pk_fma_f32 v[2:3], v[2:3], v[160:161], v[86:87] op_sel_hi:[1,0,1]
	v_pk_fma_f32 v[4:5], v[4:5], v[160:161], v[88:89] op_sel_hi:[1,0,1]
	s_and_b64 vcc, exec, s[36:37]
	v_pk_mul_f32 v[14:15], v[14:15], v[18:19]
	s_mov_b32 s42, s4
	v_pk_mul_f32 v[10:11], v[10:11], v[14:15]
	v_pk_fma_f32 v[14:15], v[16:17], v[160:161], v[100:101] op_sel_hi:[1,0,1]
	s_mov_b32 s12, s6
	v_mul_f32_e32 v16, 0xbfb8aa3b, v14
	v_mul_f32_e32 v17, 0xbfb8aa3b, v15
	v_exp_f32_e32 v16, v16
	v_exp_f32_e32 v17, v17
	s_mov_b64 s[16:17], s[10:11]
	v_add_f32_e32 v16, 1.0, v16
	v_add_f32_e32 v17, 1.0, v17
	v_rcp_f32_e32 v16, v16
	v_rcp_f32_e32 v17, v17
	s_nop 0
	v_pk_mul_f32 v[14:15], v[14:15], v[16:17]
	s_nop 0
	v_pk_mul_f32 v[12:13], v[12:13], v[14:15]
	v_mul_f32_e32 v14, 0xbfb8aa3b, v6
	v_mul_f32_e32 v15, 0xbfb8aa3b, v7
	v_exp_f32_e32 v14, v14
	v_exp_f32_e32 v15, v15
	v_add_f32_e32 v14, 1.0, v14
	v_add_f32_e32 v15, 1.0, v15
	v_rcp_f32_e32 v14, v14
	v_rcp_f32_e32 v15, v15
	s_nop 0
	v_pk_mul_f32 v[6:7], v[6:7], v[14:15]
	s_nop 0
	v_pk_mul_f32 v[6:7], v[2:3], v[6:7]
	v_pk_fma_f32 v[2:3], v[8:9], v[160:161], v[84:85] op_sel_hi:[1,0,1]
	s_nop 0
	v_mul_f32_e32 v8, 0xbfb8aa3b, v2
	v_mul_f32_e32 v9, 0xbfb8aa3b, v3
	v_exp_f32_e32 v8, v8
	v_exp_f32_e32 v9, v9
	v_add_f32_e32 v8, 1.0, v8
	v_add_f32_e32 v9, 1.0, v9
	v_rcp_f32_e32 v8, v8
	v_rcp_f32_e32 v9, v9
	s_nop 0
	v_pk_mul_f32 v[2:3], v[2:3], v[8:9]
	s_nop 0
	v_pk_mul_f32 v[8:9], v[4:5], v[2:3]
	v_cvt_pk_bf16_f32 v4, v6, v7
	v_lshrrev_b32_e32 v6, 8, v175
	v_mad_i32_i24 v6, v6, 44, v161
	v_ashrrev_i32_e32 v7, 31, v6
	v_cvt_pk_bf16_f32 v5, v8, v9
	v_lshlrev_b64 v[6:7], 15, v[6:7]
	v_lshlrev_b32_e32 v8, 7, v175
	v_lshl_add_u64 v[6:7], s[14:15], 0, v[6:7]
	v_and_b32_e32 v8, 0x7f80, v8
	v_mov_b32_e32 v9, v0
	v_lshl_add_u64 v[6:7], v[6:7], 0, v[8:9]
	v_cvt_pk_bf16_f32 v2, v10, v11
	v_cvt_pk_bf16_f32 v3, v12, v13
	v_lshl_add_u64 v[6:7], v[6:7], 0, v[130:131]
	s_mov_b64 s[14:15], s[8:9]
	global_store_dwordx4 v[6:7], v[2:5], off sc1
	s_cbranch_vccnz .LBB0_167

.LBB0_558:
	s_lshl_b32 s5, s12, 8
	v_mov_b32_e32 v82, v171
	v_mov_b32_e32 v83, v1
	s_add_i32 s5, s5, s31
	s_nop 0
	v_add_u32_e32 v182, s5, v82
	s_lshl_b32 s5, s42, 7
	s_or_b32 s5, s5, s34
	v_lshl_add_u32 v186, v83, 3, s5
	s_ashr_i32 s5, s12, 5
	s_mul_hi_i32 s7, s5, 0x5800
	s_mulk_i32 s5, 0x5800
	s_add_u32 s14, s28, s5
	s_addc_u32 s15, s29, s7
	v_ashrrev_i32_e32 v187, 31, v186
	v_lshl_add_u64 v[86:87], v[186:187], 2, s[14:15]
	s_mov_b64 s[14:15], 0x2c00
	s_movk_i32 s5, 0x2000
	global_load_dwordx4 v[82:85], v[86:87], off offset:16
	global_load_dwordx4 v[98:101], v[86:87], off
	v_lshl_add_u64 v[88:89], v[86:87], 0, s[14:15]
	v_add_co_u32_e32 v86, vcc, s5, v86
	v_ashrrev_i32_e32 v183, 31, v182
	s_nop 0
	v_addc_co_u32_e32 v87, vcc, 0, v87, vcc
	v_lshl_add_u64 v[160:161], v[182:183], 2, s[0:1]
	global_load_dwordx4 v[102:105], v[86:87], off offset:3072
	s_nop 0
	global_load_dwordx4 v[86:89], v[88:89], off offset:16
	v_add_u32_e32 v187, 16, v182
	global_load_dword v158, v[160:161], off
	v_add_u32_e32 v185, 32, v182
	v_add_u32_e32 v183, 48, v182
	v_add_u32_e32 v181, 0x80, v182
	v_add_u32_e32 v179, 0x90, v182
	v_add_u32_e32 v177, 0xa0, v182
	v_add_u32_e32 v175, 0xb0, v182
	s_waitcnt vmcnt(0)
	v_fmamk_f32 v158, v158, 0x3a800000, v223
	v_cmp_gt_f32_e32 vcc, s95, v158
	v_mul_f32_e32 v168, 0x4b800000, v158
	s_nop 0
	v_cndmask_b32_e32 v158, v158, v168, vcc
	v_rsq_f32_e32 v158, v158
	s_nop 0
	v_mul_f32_e32 v168, 0x45800000, v158
	v_cndmask_b32_e32 v184, v158, v168, vcc
	global_load_dword v158, v[160:161], off offset:64
	s_waitcnt vmcnt(0)
	v_fmamk_f32 v158, v158, 0x3a800000, v223
	v_cmp_gt_f32_e32 vcc, s95, v158
	v_mul_f32_e32 v168, 0x4b800000, v158
	s_nop 0
	v_cndmask_b32_e32 v158, v158, v168, vcc
	v_rsq_f32_e32 v158, v158
	s_nop 0
	v_mul_f32_e32 v168, 0x45800000, v158
	v_cndmask_b32_e32 v180, v158, v168, vcc
	global_load_dword v158, v[160:161], off offset:128
	s_waitcnt vmcnt(0)
	v_fmamk_f32 v158, v158, 0x3a800000, v223
	v_cmp_gt_f32_e32 vcc, s95, v158
	v_mul_f32_e32 v168, 0x4b800000, v158
	s_nop 0
	v_cndmask_b32_e32 v158, v158, v168, vcc
	v_rsq_f32_e32 v158, v158
	s_nop 0
	v_mul_f32_e32 v168, 0x45800000, v158
	v_cndmask_b32_e32 v178, v158, v168, vcc
	global_load_dword v158, v[160:161], off offset:192
	s_waitcnt vmcnt(0)
	v_fmamk_f32 v158, v158, 0x3a800000, v223
	v_cmp_gt_f32_e32 vcc, s95, v158
	v_mul_f32_e32 v168, 0x4b800000, v158
	s_nop 0
	v_cndmask_b32_e32 v158, v158, v168, vcc
	v_rsq_f32_e32 v158, v158
	s_nop 0
	v_mul_f32_e32 v168, 0x45800000, v158
	v_cndmask_b32_e32 v176, v158, v168, vcc
	global_load_dword v158, v[160:161], off offset:512
	s_waitcnt vmcnt(0)
	v_fmamk_f32 v158, v158, 0x3a800000, v223
	v_cmp_gt_f32_e32 vcc, s95, v158
	v_mul_f32_e32 v168, 0x4b800000, v158
	s_nop 0
	v_cndmask_b32_e32 v158, v158, v168, vcc
	v_rsq_f32_e32 v158, v158
	s_nop 0
	v_mul_f32_e32 v168, 0x45800000, v158
	v_cndmask_b32_e32 v174, v158, v168, vcc
	global_load_dword v158, v[160:161], off offset:576
	s_waitcnt vmcnt(0)
	v_fmamk_f32 v158, v158, 0x3a800000, v223
	v_cmp_gt_f32_e32 vcc, s95, v158
	v_mul_f32_e32 v168, 0x4b800000, v158
	s_nop 0
	v_cndmask_b32_e32 v158, v158, v168, vcc
	v_rsq_f32_e32 v158, v158
	s_nop 0
	v_mul_f32_e32 v168, 0x45800000, v158
	v_cndmask_b32_e32 v172, v158, v168, vcc
	global_load_dword v158, v[160:161], off offset:640
	s_waitcnt vmcnt(0)
	v_fmamk_f32 v158, v158, 0x3a800000, v223
	global_load_dword v160, v[160:161], off offset:704
	v_cmp_gt_f32_e32 vcc, s95, v158
	v_mul_f32_e32 v168, 0x4b800000, v158
	s_waitcnt vmcnt(0)
	v_fmamk_f32 v160, v160, 0x3a800000, v223
	v_cndmask_b32_e32 v158, v158, v168, vcc
	v_rsq_f32_e32 v158, v158
	v_mul_f32_e32 v161, 0x4b800000, v160
	v_mul_f32_e32 v168, 0x45800000, v158
	v_cndmask_b32_e32 v158, v158, v168, vcc
	v_cmp_gt_f32_e32 vcc, s95, v160
	s_nop 1
	v_cndmask_b32_e32 v160, v160, v161, vcc
	v_rsq_f32_e32 v160, v160
	s_nop 0
	v_mul_f32_e32 v161, 0x45800000, v160
	v_cndmask_b32_e32 v160, v160, v161, vcc
	v_ashrrev_i32_e32 v161, 6, v186
	v_and_b32_e32 v186, 56, v186
	v_pk_fma_f32 v[138:139], v[138:139], v[184:185], v[98:99] op_sel_hi:[1,0,1]
	v_pk_fma_f32 v[142:143], v[142:143], v[184:185], v[102:103] op_sel_hi:[1,0,1]
	v_mul_f32_e32 v168, 0xbfb8aa3b, v138
	v_mul_f32_e32 v169, 0xbfb8aa3b, v139
	v_exp_f32_e32 v168, v168
	v_exp_f32_e32 v169, v169
	v_pk_fma_f32 v[140:141], v[140:141], v[184:185], v[100:101] op_sel_hi:[1,0,1]
	v_pk_fma_f32 v[134:135], v[134:135], v[184:185], v[82:83] op_sel_hi:[1,0,1]
	v_add_f32_e32 v168, 1.0, v168
	v_add_f32_e32 v169, 1.0, v169
	v_rcp_f32_e32 v168, v168
	v_rcp_f32_e32 v169, v169
	v_pk_fma_f32 v[130:131], v[130:131], v[184:185], v[86:87] op_sel_hi:[1,0,1]
	v_pk_fma_f32 v[132:133], v[132:133], v[184:185], v[88:89] op_sel_hi:[1,0,1]
	v_readlane_b32 s14, v254, 27
	v_pk_mul_f32 v[138:139], v[138:139], v[168:169]
	v_readlane_b32 s15, v254, 28
	v_pk_mul_f32 v[138:139], v[142:143], v[138:139]
	v_pk_fma_f32 v[142:143], v[144:145], v[184:185], v[104:105] op_sel_hi:[1,0,1]
	v_mul_f32_e32 v144, 0xbfb8aa3b, v140
	v_mul_f32_e32 v145, 0xbfb8aa3b, v141
	v_exp_f32_e32 v144, v144
	v_exp_f32_e32 v145, v145
	v_add_f32_e32 v144, 1.0, v144
	v_add_f32_e32 v145, 1.0, v145
	v_rcp_f32_e32 v144, v144
	v_rcp_f32_e32 v145, v145
	s_nop 0
	v_pk_mul_f32 v[140:141], v[140:141], v[144:145]
	s_nop 0
	v_pk_mul_f32 v[140:141], v[142:143], v[140:141]
	v_mul_f32_e32 v142, 0xbfb8aa3b, v134
	v_mul_f32_e32 v143, 0xbfb8aa3b, v135
	v_exp_f32_e32 v142, v142
	v_exp_f32_e32 v143, v143
	v_add_f32_e32 v142, 1.0, v142
	v_add_f32_e32 v143, 1.0, v143
	v_rcp_f32_e32 v142, v142
	v_rcp_f32_e32 v143, v143
	s_nop 0
	v_pk_mul_f32 v[134:135], v[134:135], v[142:143]
	s_nop 0
	v_pk_mul_f32 v[130:131], v[130:131], v[134:135]
	v_pk_fma_f32 v[134:135], v[136:137], v[184:185], v[84:85] op_sel_hi:[1,0,1]
	s_nop 0
	v_mul_f32_e32 v136, 0xbfb8aa3b, v134
	v_mul_f32_e32 v137, 0xbfb8aa3b, v135
	v_exp_f32_e32 v136, v136
	v_exp_f32_e32 v137, v137
	v_add_f32_e32 v136, 1.0, v136
	v_add_f32_e32 v137, 1.0, v137
	v_rcp_f32_e32 v136, v136
	v_rcp_f32_e32 v137, v137
	s_nop 0
	v_pk_mul_f32 v[134:135], v[134:135], v[136:137]
	s_nop 0
	v_pk_mul_f32 v[136:137], v[132:133], v[134:135]
	v_cvt_pk_bf16_f32 v134, v130, v131
	v_lshrrev_b32_e32 v130, 8, v182
	v_mad_i32_i24 v130, v130, 44, v161
	v_ashrrev_i32_e32 v131, 31, v130
	v_cvt_pk_bf16_f32 v135, v136, v137
	v_lshlrev_b64 v[130:131], 15, v[130:131]
	v_lshlrev_b32_e32 v136, 7, v182
	v_lshl_add_u64 v[130:131], s[14:15], 0, v[130:131]
	v_and_b32_e32 v136, 0x7f80, v136
	v_mov_b32_e32 v137, v0
	v_lshl_add_u64 v[136:137], v[130:131], 0, v[136:137]
	v_lshlrev_b32_e32 v130, 1, v186
	v_mov_b32_e32 v131, v0
	v_cvt_pk_bf16_f32 v132, v138, v139
	v_cvt_pk_bf16_f32 v133, v140, v141
	v_lshl_add_u64 v[136:137], v[136:137], 0, v[130:131]
	global_store_dwordx4 v[136:137], v[132:135], off sc1
	v_pk_fma_f32 v[126:127], v[126:127], v[180:181], v[98:99] op_sel_hi:[1,0,1]
	v_pk_fma_f32 v[122:123], v[122:123], v[180:181], v[102:103] op_sel_hi:[1,0,1]
	v_mul_f32_e32 v132, 0xbfb8aa3b, v126
	v_mul_f32_e32 v133, 0xbfb8aa3b, v127
	v_exp_f32_e32 v132, v132
	v_exp_f32_e32 v133, v133
	v_pk_fma_f32 v[124:125], v[124:125], v[180:181], v[104:105] op_sel_hi:[1,0,1]
	v_pk_fma_f32 v[118:119], v[118:119], v[180:181], v[82:83] op_sel_hi:[1,0,1]
	v_add_f32_e32 v132, 1.0, v132
	v_add_f32_e32 v133, 1.0, v133
	v_rcp_f32_e32 v132, v132
	v_rcp_f32_e32 v133, v133
	v_pk_fma_f32 v[114:115], v[114:115], v[180:181], v[86:87] op_sel_hi:[1,0,1]
	v_pk_fma_f32 v[116:117], v[116:117], v[180:181], v[88:89] op_sel_hi:[1,0,1]
	v_pk_mul_f32 v[126:127], v[126:127], v[132:133]
	s_nop 0
	v_pk_mul_f32 v[122:123], v[122:123], v[126:127]
	v_pk_fma_f32 v[126:127], v[128:129], v[180:181], v[100:101] op_sel_hi:[1,0,1]
	s_nop 0
	v_mul_f32_e32 v128, 0xbfb8aa3b, v126
	v_mul_f32_e32 v129, 0xbfb8aa3b, v127
	v_exp_f32_e32 v128, v128
	v_exp_f32_e32 v129, v129
	v_add_f32_e32 v128, 1.0, v128
	v_add_f32_e32 v129, 1.0, v129
	v_rcp_f32_e32 v128, v128
	v_rcp_f32_e32 v129, v129
	s_nop 0
	v_pk_mul_f32 v[126:127], v[126:127], v[128:129]
	s_nop 0
	v_pk_mul_f32 v[124:125], v[124:125], v[126:127]
	v_mul_f32_e32 v126, 0xbfb8aa3b, v118
	v_mul_f32_e32 v127, 0xbfb8aa3b, v119
	v_exp_f32_e32 v126, v126
	v_exp_f32_e32 v127, v127
	v_add_f32_e32 v126, 1.0, v126
	v_add_f32_e32 v127, 1.0, v127
	v_rcp_f32_e32 v126, v126
	v_rcp_f32_e32 v127, v127
	s_nop 0
	v_pk_mul_f32 v[118:119], v[118:119], v[126:127]
	s_nop 0
	v_pk_mul_f32 v[118:119], v[114:115], v[118:119]
	v_pk_fma_f32 v[114:115], v[120:121], v[180:181], v[84:85] op_sel_hi:[1,0,1]
	s_nop 0
	v_mul_f32_e32 v120, 0xbfb8aa3b, v114
	v_mul_f32_e32 v121, 0xbfb8aa3b, v115
	v_exp_f32_e32 v120, v120
	v_exp_f32_e32 v121, v121
	v_add_f32_e32 v120, 1.0, v120
	v_add_f32_e32 v121, 1.0, v121
	v_rcp_f32_e32 v120, v120
	v_rcp_f32_e32 v121, v121
	s_nop 0
	v_pk_mul_f32 v[114:115], v[114:115], v[120:121]
	s_nop 0
	v_pk_mul_f32 v[120:121], v[116:117], v[114:115]
	v_cvt_pk_bf16_f32 v116, v118, v119
	v_lshrrev_b32_e32 v118, 8, v187
	v_mad_i32_i24 v118, v118, 44, v161
	v_ashrrev_i32_e32 v119, 31, v118
	v_cvt_pk_bf16_f32 v117, v120, v121
	v_lshlrev_b64 v[118:119], 15, v[118:119]
	v_lshlrev_b32_e32 v120, 7, v187
	v_lshl_add_u64 v[118:119], s[14:15], 0, v[118:119]
	v_and_b32_e32 v120, 0x7f80, v120
	v_mov_b32_e32 v121, v0
	v_lshl_add_u64 v[118:119], v[118:119], 0, v[120:121]
	v_cvt_pk_bf16_f32 v114, v122, v123
	v_cvt_pk_bf16_f32 v115, v124, v125
	v_lshl_add_u64 v[118:119], v[118:119], 0, v[130:131]
	global_store_dwordx4 v[118:119], v[114:117], off sc1
	v_pk_fma_f32 v[110:111], v[110:111], v[178:179], v[98:99] op_sel_hi:[1,0,1]
	v_pk_fma_f32 v[106:107], v[106:107], v[178:179], v[102:103] op_sel_hi:[1,0,1]
	v_mul_f32_e32 v114, 0xbfb8aa3b, v110
	v_mul_f32_e32 v115, 0xbfb8aa3b, v111
	v_exp_f32_e32 v114, v114
	v_exp_f32_e32 v115, v115
	v_pk_fma_f32 v[108:109], v[108:109], v[178:179], v[104:105] op_sel_hi:[1,0,1]
	v_pk_fma_f32 v[94:95], v[94:95], v[178:179], v[82:83] op_sel_hi:[1,0,1]
	v_add_f32_e32 v114, 1.0, v114
	v_add_f32_e32 v115, 1.0, v115
	v_rcp_f32_e32 v114, v114
	v_rcp_f32_e32 v115, v115
	v_pk_fma_f32 v[90:91], v[90:91], v[178:179], v[86:87] op_sel_hi:[1,0,1]
	v_pk_fma_f32 v[92:93], v[92:93], v[178:179], v[88:89] op_sel_hi:[1,0,1]
	v_pk_mul_f32 v[110:111], v[110:111], v[114:115]
	s_nop 0
	v_pk_mul_f32 v[106:107], v[106:107], v[110:111]
	v_pk_fma_f32 v[110:111], v[112:113], v[178:179], v[100:101] op_sel_hi:[1,0,1]
	s_nop 0
	v_mul_f32_e32 v112, 0xbfb8aa3b, v110
	v_mul_f32_e32 v113, 0xbfb8aa3b, v111
	v_exp_f32_e32 v112, v112
	v_exp_f32_e32 v113, v113
	v_add_f32_e32 v112, 1.0, v112
	v_add_f32_e32 v113, 1.0, v113
	v_rcp_f32_e32 v112, v112
	v_rcp_f32_e32 v113, v113
	s_nop 0
	v_pk_mul_f32 v[110:111], v[110:111], v[112:113]
	s_nop 0
	v_pk_mul_f32 v[108:109], v[108:109], v[110:111]
	v_mul_f32_e32 v110, 0xbfb8aa3b, v94
	v_mul_f32_e32 v111, 0xbfb8aa3b, v95
	v_exp_f32_e32 v110, v110
	v_exp_f32_e32 v111, v111
	v_add_f32_e32 v110, 1.0, v110
	v_add_f32_e32 v111, 1.0, v111
	v_rcp_f32_e32 v110, v110
	v_rcp_f32_e32 v111, v111
	s_nop 0
	v_pk_mul_f32 v[94:95], v[94:95], v[110:111]
	s_nop 0
	v_pk_mul_f32 v[94:95], v[90:91], v[94:95]
	v_pk_fma_f32 v[90:91], v[96:97], v[178:179], v[84:85] op_sel_hi:[1,0,1]
	s_nop 0
	v_mul_f32_e32 v96, 0xbfb8aa3b, v90
	v_mul_f32_e32 v97, 0xbfb8aa3b, v91
	v_exp_f32_e32 v96, v96
	v_exp_f32_e32 v97, v97
	v_add_f32_e32 v96, 1.0, v96
	v_add_f32_e32 v97, 1.0, v97
	v_rcp_f32_e32 v96, v96
	v_rcp_f32_e32 v97, v97
	s_nop 0
	v_pk_mul_f32 v[90:91], v[90:91], v[96:97]
	s_nop 0
	v_pk_mul_f32 v[96:97], v[92:93], v[90:91]
	v_cvt_pk_bf16_f32 v92, v94, v95
	v_lshrrev_b32_e32 v94, 8, v185
	v_mad_i32_i24 v94, v94, 44, v161
	v_ashrrev_i32_e32 v95, 31, v94
	v_cvt_pk_bf16_f32 v93, v96, v97
	v_lshlrev_b64 v[94:95], 15, v[94:95]
	v_lshlrev_b32_e32 v96, 7, v185
	v_lshl_add_u64 v[94:95], s[14:15], 0, v[94:95]
	v_and_b32_e32 v96, 0x7f80, v96
	v_mov_b32_e32 v97, v0
	v_lshl_add_u64 v[94:95], v[94:95], 0, v[96:97]
	v_cvt_pk_bf16_f32 v90, v106, v107
	v_cvt_pk_bf16_f32 v91, v108, v109
	v_lshl_add_u64 v[94:95], v[94:95], 0, v[130:131]
	global_store_dwordx4 v[94:95], v[90:93], off sc1
	v_pk_fma_f32 v[78:79], v[78:79], v[176:177], v[98:99] op_sel_hi:[1,0,1]
	v_pk_fma_f32 v[74:75], v[74:75], v[176:177], v[102:103] op_sel_hi:[1,0,1]
	v_mul_f32_e32 v90, 0xbfb8aa3b, v78
	v_mul_f32_e32 v91, 0xbfb8aa3b, v79
	v_exp_f32_e32 v90, v90
	v_exp_f32_e32 v91, v91
	v_pk_fma_f32 v[76:77], v[76:77], v[176:177], v[104:105] op_sel_hi:[1,0,1]
	v_pk_fma_f32 v[70:71], v[70:71], v[176:177], v[82:83] op_sel_hi:[1,0,1]
	v_add_f32_e32 v90, 1.0, v90
	v_add_f32_e32 v91, 1.0, v91
	v_rcp_f32_e32 v90, v90
	v_rcp_f32_e32 v91, v91
	v_pk_fma_f32 v[66:67], v[66:67], v[176:177], v[86:87] op_sel_hi:[1,0,1]
	v_pk_fma_f32 v[68:69], v[68:69], v[176:177], v[88:89] op_sel_hi:[1,0,1]
	v_pk_mul_f32 v[78:79], v[78:79], v[90:91]
	s_nop 0
	v_pk_mul_f32 v[74:75], v[74:75], v[78:79]
	v_pk_fma_f32 v[78:79], v[80:81], v[176:177], v[100:101] op_sel_hi:[1,0,1]
	s_nop 0
	v_mul_f32_e32 v80, 0xbfb8aa3b, v78
	v_mul_f32_e32 v81, 0xbfb8aa3b, v79
	v_exp_f32_e32 v80, v80
	v_exp_f32_e32 v81, v81
	v_add_f32_e32 v80, 1.0, v80
	v_add_f32_e32 v81, 1.0, v81
	v_rcp_f32_e32 v80, v80
	v_rcp_f32_e32 v81, v81
	s_nop 0
	v_pk_mul_f32 v[78:79], v[78:79], v[80:81]
	s_nop 0
	v_pk_mul_f32 v[76:77], v[76:77], v[78:79]
	v_mul_f32_e32 v78, 0xbfb8aa3b, v70
	v_mul_f32_e32 v79, 0xbfb8aa3b, v71
	v_exp_f32_e32 v78, v78
	v_exp_f32_e32 v79, v79
	v_add_f32_e32 v78, 1.0, v78
	v_add_f32_e32 v79, 1.0, v79
	v_rcp_f32_e32 v78, v78
	v_rcp_f32_e32 v79, v79
	s_nop 0
	v_pk_mul_f32 v[70:71], v[70:71], v[78:79]
	s_nop 0
	v_pk_mul_f32 v[70:71], v[66:67], v[70:71]
	v_pk_fma_f32 v[66:67], v[72:73], v[176:177], v[84:85] op_sel_hi:[1,0,1]
	s_nop 0
	v_mul_f32_e32 v72, 0xbfb8aa3b, v66
	v_mul_f32_e32 v73, 0xbfb8aa3b, v67
	v_exp_f32_e32 v72, v72
	v_exp_f32_e32 v73, v73
	v_add_f32_e32 v72, 1.0, v72
	v_add_f32_e32 v73, 1.0, v73
	v_rcp_f32_e32 v72, v72
	v_rcp_f32_e32 v73, v73
	s_nop 0
	v_pk_mul_f32 v[66:67], v[66:67], v[72:73]
	s_nop 0
	v_pk_mul_f32 v[72:73], v[68:69], v[66:67]
	v_cvt_pk_bf16_f32 v68, v70, v71
	v_lshrrev_b32_e32 v70, 8, v183
	v_mad_i32_i24 v70, v70, 44, v161
	v_ashrrev_i32_e32 v71, 31, v70
	v_cvt_pk_bf16_f32 v69, v72, v73
	v_lshlrev_b64 v[70:71], 15, v[70:71]
	v_lshlrev_b32_e32 v72, 7, v183
	v_lshl_add_u64 v[70:71], s[14:15], 0, v[70:71]
	v_and_b32_e32 v72, 0x7f80, v72
	v_mov_b32_e32 v73, v0
	v_lshl_add_u64 v[70:71], v[70:71], 0, v[72:73]
	v_cvt_pk_bf16_f32 v66, v74, v75
	v_cvt_pk_bf16_f32 v67, v76, v77
	v_lshl_add_u64 v[70:71], v[70:71], 0, v[130:131]
	global_store_dwordx4 v[70:71], v[66:69], off sc1
	v_pk_fma_f32 v[62:63], v[62:63], v[174:175], v[98:99] op_sel_hi:[1,0,1]
	v_pk_fma_f32 v[58:59], v[58:59], v[174:175], v[102:103] op_sel_hi:[1,0,1]
	v_mul_f32_e32 v66, 0xbfb8aa3b, v62
	v_mul_f32_e32 v67, 0xbfb8aa3b, v63
	v_exp_f32_e32 v66, v66
	v_exp_f32_e32 v67, v67
	v_pk_fma_f32 v[60:61], v[60:61], v[174:175], v[104:105] op_sel_hi:[1,0,1]
	v_pk_fma_f32 v[54:55], v[54:55], v[174:175], v[82:83] op_sel_hi:[1,0,1]
	v_add_f32_e32 v66, 1.0, v66
	v_add_f32_e32 v67, 1.0, v67
	v_rcp_f32_e32 v66, v66
	v_rcp_f32_e32 v67, v67
	v_pk_fma_f32 v[50:51], v[50:51], v[174:175], v[86:87] op_sel_hi:[1,0,1]
	v_pk_fma_f32 v[52:53], v[52:53], v[174:175], v[88:89] op_sel_hi:[1,0,1]
	v_pk_mul_f32 v[62:63], v[62:63], v[66:67]
	s_nop 0
	v_pk_mul_f32 v[58:59], v[58:59], v[62:63]
	v_pk_fma_f32 v[62:63], v[64:65], v[174:175], v[100:101] op_sel_hi:[1,0,1]
	s_nop 0
	v_mul_f32_e32 v64, 0xbfb8aa3b, v62
	v_mul_f32_e32 v65, 0xbfb8aa3b, v63
	v_exp_f32_e32 v64, v64
	v_exp_f32_e32 v65, v65
	v_add_f32_e32 v64, 1.0, v64
	v_add_f32_e32 v65, 1.0, v65
	v_rcp_f32_e32 v64, v64
	v_rcp_f32_e32 v65, v65
	s_nop 0
	v_pk_mul_f32 v[62:63], v[62:63], v[64:65]
	s_nop 0
	v_pk_mul_f32 v[60:61], v[60:61], v[62:63]
	v_mul_f32_e32 v62, 0xbfb8aa3b, v54
	v_mul_f32_e32 v63, 0xbfb8aa3b, v55
	v_exp_f32_e32 v62, v62
	v_exp_f32_e32 v63, v63
	v_add_f32_e32 v62, 1.0, v62
	v_add_f32_e32 v63, 1.0, v63
	v_rcp_f32_e32 v62, v62
	v_rcp_f32_e32 v63, v63
	s_nop 0
	v_pk_mul_f32 v[54:55], v[54:55], v[62:63]
	s_nop 0
	v_pk_mul_f32 v[54:55], v[50:51], v[54:55]
	v_pk_fma_f32 v[50:51], v[56:57], v[174:175], v[84:85] op_sel_hi:[1,0,1]
	s_nop 0
	v_mul_f32_e32 v56, 0xbfb8aa3b, v50
	v_mul_f32_e32 v57, 0xbfb8aa3b, v51
	v_exp_f32_e32 v56, v56
	v_exp_f32_e32 v57, v57
	v_add_f32_e32 v56, 1.0, v56
	v_add_f32_e32 v57, 1.0, v57
	v_rcp_f32_e32 v56, v56
	v_rcp_f32_e32 v57, v57
	s_nop 0
	v_pk_mul_f32 v[50:51], v[50:51], v[56:57]
	s_nop 0
	v_pk_mul_f32 v[56:57], v[52:53], v[50:51]
	v_cvt_pk_bf16_f32 v52, v54, v55
	v_lshrrev_b32_e32 v54, 8, v181
	v_mad_i32_i24 v54, v54, 44, v161
	v_ashrrev_i32_e32 v55, 31, v54
	v_cvt_pk_bf16_f32 v53, v56, v57
	v_lshlrev_b64 v[54:55], 15, v[54:55]
	v_lshlrev_b32_e32 v56, 7, v181
	v_lshl_add_u64 v[54:55], s[14:15], 0, v[54:55]
	v_and_b32_e32 v56, 0x7f80, v56
	v_mov_b32_e32 v57, v0
	v_lshl_add_u64 v[54:55], v[54:55], 0, v[56:57]
	v_cvt_pk_bf16_f32 v50, v58, v59
	v_cvt_pk_bf16_f32 v51, v60, v61
	v_lshl_add_u64 v[54:55], v[54:55], 0, v[130:131]
	global_store_dwordx4 v[54:55], v[50:53], off sc1
	v_pk_fma_f32 v[46:47], v[46:47], v[172:173], v[98:99] op_sel_hi:[1,0,1]
	v_pk_fma_f32 v[42:43], v[42:43], v[172:173], v[102:103] op_sel_hi:[1,0,1]
	v_mul_f32_e32 v50, 0xbfb8aa3b, v46
	v_mul_f32_e32 v51, 0xbfb8aa3b, v47
	v_exp_f32_e32 v50, v50
	v_exp_f32_e32 v51, v51
	v_pk_fma_f32 v[44:45], v[44:45], v[172:173], v[104:105] op_sel_hi:[1,0,1]
	v_pk_fma_f32 v[38:39], v[38:39], v[172:173], v[82:83] op_sel_hi:[1,0,1]
	v_add_f32_e32 v50, 1.0, v50
	v_add_f32_e32 v51, 1.0, v51
	v_rcp_f32_e32 v50, v50
	v_rcp_f32_e32 v51, v51
	v_pk_fma_f32 v[34:35], v[34:35], v[172:173], v[86:87] op_sel_hi:[1,0,1]
	v_pk_fma_f32 v[36:37], v[36:37], v[172:173], v[88:89] op_sel_hi:[1,0,1]
	v_pk_mul_f32 v[46:47], v[46:47], v[50:51]
	s_nop 0
	v_pk_mul_f32 v[42:43], v[42:43], v[46:47]
	v_pk_fma_f32 v[46:47], v[48:49], v[172:173], v[100:101] op_sel_hi:[1,0,1]
	s_nop 0
	v_mul_f32_e32 v48, 0xbfb8aa3b, v46
	v_mul_f32_e32 v49, 0xbfb8aa3b, v47
	v_exp_f32_e32 v48, v48
	v_exp_f32_e32 v49, v49
	v_add_f32_e32 v48, 1.0, v48
	v_add_f32_e32 v49, 1.0, v49
	v_rcp_f32_e32 v48, v48
	v_rcp_f32_e32 v49, v49
	s_nop 0
	v_pk_mul_f32 v[46:47], v[46:47], v[48:49]
	s_nop 0
	v_pk_mul_f32 v[44:45], v[44:45], v[46:47]
	v_mul_f32_e32 v46, 0xbfb8aa3b, v38
	v_mul_f32_e32 v47, 0xbfb8aa3b, v39
	v_exp_f32_e32 v46, v46
	v_exp_f32_e32 v47, v47
	v_add_f32_e32 v46, 1.0, v46
	v_add_f32_e32 v47, 1.0, v47
	v_rcp_f32_e32 v46, v46
	v_rcp_f32_e32 v47, v47
	s_nop 0
	v_pk_mul_f32 v[38:39], v[38:39], v[46:47]
	s_nop 0
	v_pk_mul_f32 v[38:39], v[34:35], v[38:39]
	v_pk_fma_f32 v[34:35], v[40:41], v[172:173], v[84:85] op_sel_hi:[1,0,1]
	s_nop 0
	v_mul_f32_e32 v40, 0xbfb8aa3b, v34
	v_mul_f32_e32 v41, 0xbfb8aa3b, v35
	v_exp_f32_e32 v40, v40
	v_exp_f32_e32 v41, v41
	v_add_f32_e32 v40, 1.0, v40
	v_add_f32_e32 v41, 1.0, v41
	v_rcp_f32_e32 v40, v40
	v_rcp_f32_e32 v41, v41
	s_nop 0
	v_pk_mul_f32 v[34:35], v[34:35], v[40:41]
	s_nop 0
	v_pk_mul_f32 v[40:41], v[36:37], v[34:35]
	v_cvt_pk_bf16_f32 v36, v38, v39
	v_lshrrev_b32_e32 v38, 8, v179
	v_mad_i32_i24 v38, v38, 44, v161
	v_ashrrev_i32_e32 v39, 31, v38
	v_cvt_pk_bf16_f32 v37, v40, v41
	v_lshlrev_b64 v[38:39], 15, v[38:39]
	v_lshlrev_b32_e32 v40, 7, v179
	v_lshl_add_u64 v[38:39], s[14:15], 0, v[38:39]
	v_and_b32_e32 v40, 0x7f80, v40
	v_mov_b32_e32 v41, v0
	v_lshl_add_u64 v[38:39], v[38:39], 0, v[40:41]
	v_cvt_pk_bf16_f32 v34, v42, v43
	v_cvt_pk_bf16_f32 v35, v44, v45
	v_lshl_add_u64 v[38:39], v[38:39], 0, v[130:131]
	global_store_dwordx4 v[38:39], v[34:37], off sc1
	v_pk_fma_f32 v[30:31], v[30:31], v[158:159], v[98:99] op_sel_hi:[1,0,1]
	v_pk_fma_f32 v[26:27], v[26:27], v[158:159], v[102:103] op_sel_hi:[1,0,1]
	v_mul_f32_e32 v34, 0xbfb8aa3b, v30
	v_mul_f32_e32 v35, 0xbfb8aa3b, v31
	v_exp_f32_e32 v34, v34
	v_exp_f32_e32 v35, v35
	v_pk_fma_f32 v[28:29], v[28:29], v[158:159], v[104:105] op_sel_hi:[1,0,1]
	v_pk_fma_f32 v[22:23], v[22:23], v[158:159], v[82:83] op_sel_hi:[1,0,1]
	v_add_f32_e32 v34, 1.0, v34
	v_add_f32_e32 v35, 1.0, v35
	v_rcp_f32_e32 v34, v34
	v_rcp_f32_e32 v35, v35
	v_pk_fma_f32 v[18:19], v[18:19], v[158:159], v[86:87] op_sel_hi:[1,0,1]
	v_pk_fma_f32 v[20:21], v[20:21], v[158:159], v[88:89] op_sel_hi:[1,0,1]
	v_pk_mul_f32 v[30:31], v[30:31], v[34:35]
	s_nop 0
	v_pk_mul_f32 v[26:27], v[26:27], v[30:31]
	v_pk_fma_f32 v[30:31], v[32:33], v[158:159], v[100:101] op_sel_hi:[1,0,1]
	s_nop 0
	v_mul_f32_e32 v32, 0xbfb8aa3b, v30
	v_mul_f32_e32 v33, 0xbfb8aa3b, v31
	v_exp_f32_e32 v32, v32
	v_exp_f32_e32 v33, v33
	v_add_f32_e32 v32, 1.0, v32
	v_add_f32_e32 v33, 1.0, v33
	v_rcp_f32_e32 v32, v32
	v_rcp_f32_e32 v33, v33
	s_nop 0
	v_pk_mul_f32 v[30:31], v[30:31], v[32:33]
	s_nop 0
	v_pk_mul_f32 v[28:29], v[28:29], v[30:31]
	v_mul_f32_e32 v30, 0xbfb8aa3b, v22
	v_mul_f32_e32 v31, 0xbfb8aa3b, v23
	v_exp_f32_e32 v30, v30
	v_exp_f32_e32 v31, v31
	v_add_f32_e32 v30, 1.0, v30
	v_add_f32_e32 v31, 1.0, v31
	v_rcp_f32_e32 v30, v30
	v_rcp_f32_e32 v31, v31
	s_nop 0
	v_pk_mul_f32 v[22:23], v[22:23], v[30:31]
	s_nop 0
	v_pk_mul_f32 v[22:23], v[18:19], v[22:23]
	v_pk_fma_f32 v[18:19], v[24:25], v[158:159], v[84:85] op_sel_hi:[1,0,1]
	s_nop 0
	v_mul_f32_e32 v24, 0xbfb8aa3b, v18
	v_mul_f32_e32 v25, 0xbfb8aa3b, v19
	v_exp_f32_e32 v24, v24
	v_exp_f32_e32 v25, v25
	v_add_f32_e32 v24, 1.0, v24
	v_add_f32_e32 v25, 1.0, v25
	v_rcp_f32_e32 v24, v24
	v_rcp_f32_e32 v25, v25
	s_nop 0
	v_pk_mul_f32 v[18:19], v[18:19], v[24:25]
	s_nop 0
	v_pk_mul_f32 v[24:25], v[20:21], v[18:19]
	v_cvt_pk_bf16_f32 v20, v22, v23
	v_lshrrev_b32_e32 v22, 8, v177
	v_mad_i32_i24 v22, v22, 44, v161
	v_ashrrev_i32_e32 v23, 31, v22
	v_cvt_pk_bf16_f32 v21, v24, v25
	v_lshlrev_b64 v[22:23], 15, v[22:23]
	v_lshlrev_b32_e32 v24, 7, v177
	v_lshl_add_u64 v[22:23], s[14:15], 0, v[22:23]
	v_and_b32_e32 v24, 0x7f80, v24
	v_mov_b32_e32 v25, v0
	v_lshl_add_u64 v[22:23], v[22:23], 0, v[24:25]
	v_cvt_pk_bf16_f32 v18, v26, v27
	v_cvt_pk_bf16_f32 v19, v28, v29
	v_lshl_add_u64 v[22:23], v[22:23], 0, v[130:131]
	global_store_dwordx4 v[22:23], v[18:21], off sc1
	v_pk_fma_f32 v[14:15], v[14:15], v[160:161], v[98:99] op_sel_hi:[1,0,1]
	v_pk_fma_f32 v[10:11], v[10:11], v[160:161], v[102:103] op_sel_hi:[1,0,1]
	v_mul_f32_e32 v18, 0xbfb8aa3b, v14
	v_mul_f32_e32 v19, 0xbfb8aa3b, v15
	v_exp_f32_e32 v18, v18
	v_exp_f32_e32 v19, v19
	v_pk_fma_f32 v[12:13], v[12:13], v[160:161], v[104:105] op_sel_hi:[1,0,1]
	v_pk_fma_f32 v[6:7], v[6:7], v[160:161], v[82:83] op_sel_hi:[1,0,1]
	v_add_f32_e32 v18, 1.0, v18
	v_add_f32_e32 v19, 1.0, v19
	v_rcp_f32_e32 v18, v18
	v_rcp_f32_e32 v19, v19
	v_pk_fma_f32 v[2:3], v[2:3], v[160:161], v[86:87] op_sel_hi:[1,0,1]
	v_pk_fma_f32 v[4:5], v[4:5], v[160:161], v[88:89] op_sel_hi:[1,0,1]
	s_and_b64 vcc, exec, s[36:37]
	v_pk_mul_f32 v[14:15], v[14:15], v[18:19]
	s_mov_b32 s42, s4
	v_pk_mul_f32 v[10:11], v[10:11], v[14:15]
	v_pk_fma_f32 v[14:15], v[16:17], v[160:161], v[100:101] op_sel_hi:[1,0,1]
	s_mov_b32 s12, s6
	v_mul_f32_e32 v16, 0xbfb8aa3b, v14
	v_mul_f32_e32 v17, 0xbfb8aa3b, v15
	v_exp_f32_e32 v16, v16
	v_exp_f32_e32 v17, v17
	s_mov_b64 s[16:17], s[10:11]
	v_add_f32_e32 v16, 1.0, v16
	v_add_f32_e32 v17, 1.0, v17
	v_rcp_f32_e32 v16, v16
	v_rcp_f32_e32 v17, v17
	s_nop 0
	v_pk_mul_f32 v[14:15], v[14:15], v[16:17]
	s_nop 0
	v_pk_mul_f32 v[12:13], v[12:13], v[14:15]
	v_mul_f32_e32 v14, 0xbfb8aa3b, v6
	v_mul_f32_e32 v15, 0xbfb8aa3b, v7
	v_exp_f32_e32 v14, v14
	v_exp_f32_e32 v15, v15
	v_add_f32_e32 v14, 1.0, v14
	v_add_f32_e32 v15, 1.0, v15
	v_rcp_f32_e32 v14, v14
	v_rcp_f32_e32 v15, v15
	s_nop 0
	v_pk_mul_f32 v[6:7], v[6:7], v[14:15]
	s_nop 0
	v_pk_mul_f32 v[6:7], v[2:3], v[6:7]
	v_pk_fma_f32 v[2:3], v[8:9], v[160:161], v[84:85] op_sel_hi:[1,0,1]
	s_nop 0
	v_mul_f32_e32 v8, 0xbfb8aa3b, v2
	v_mul_f32_e32 v9, 0xbfb8aa3b, v3
	v_exp_f32_e32 v8, v8
	v_exp_f32_e32 v9, v9
	v_add_f32_e32 v8, 1.0, v8
	v_add_f32_e32 v9, 1.0, v9
	v_rcp_f32_e32 v8, v8
	v_rcp_f32_e32 v9, v9
	s_nop 0
	v_pk_mul_f32 v[2:3], v[2:3], v[8:9]
	s_nop 0
	v_pk_mul_f32 v[8:9], v[4:5], v[2:3]
	v_cvt_pk_bf16_f32 v4, v6, v7
	v_lshrrev_b32_e32 v6, 8, v175
	v_mad_i32_i24 v6, v6, 44, v161
	v_ashrrev_i32_e32 v7, 31, v6
	v_cvt_pk_bf16_f32 v5, v8, v9
	v_lshlrev_b64 v[6:7], 15, v[6:7]
	v_lshlrev_b32_e32 v8, 7, v175
	v_lshl_add_u64 v[6:7], s[14:15], 0, v[6:7]
	v_and_b32_e32 v8, 0x7f80, v8
	v_mov_b32_e32 v9, v0
	v_lshl_add_u64 v[6:7], v[6:7], 0, v[8:9]
	v_cvt_pk_bf16_f32 v2, v10, v11
	v_cvt_pk_bf16_f32 v3, v12, v13
	v_lshl_add_u64 v[6:7], v[6:7], 0, v[130:131]
	s_mov_b64 s[14:15], s[8:9]
	global_store_dwordx4 v[6:7], v[2:5], off sc1
	s_cbranch_vccnz .LBB0_564

.LBB0_619:
	s_lshl_b32 s5, s12, 8
	v_mov_b32_e32 v82, v159
	v_mov_b32_e32 v83, v1
	s_add_i32 s5, s5, s31
	s_nop 0
	v_add_u32_e32 v182, s5, v82
	s_lshl_b32 s5, s42, 7
	s_or_b32 s5, s5, s34
	v_lshl_add_u32 v186, v83, 3, s5
	s_ashr_i32 s5, s12, 5
	s_mul_hi_i32 s7, s5, 0x5800
	s_mulk_i32 s5, 0x5800
	s_add_u32 s14, s28, s5
	s_addc_u32 s15, s29, s7
	v_ashrrev_i32_e32 v187, 31, v186
	v_lshl_add_u64 v[86:87], v[186:187], 2, s[14:15]
	s_mov_b64 s[14:15], 0x2c00
	s_movk_i32 s5, 0x2000
	global_load_dwordx4 v[82:85], v[86:87], off offset:16
	global_load_dwordx4 v[98:101], v[86:87], off
	v_lshl_add_u64 v[88:89], v[86:87], 0, s[14:15]
	v_add_co_u32_e32 v86, vcc, s5, v86
	v_ashrrev_i32_e32 v183, 31, v182
	s_nop 0
	v_addc_co_u32_e32 v87, vcc, 0, v87, vcc
	v_lshl_add_u64 v[160:161], v[182:183], 2, s[0:1]
	global_load_dwordx4 v[102:105], v[86:87], off offset:3072
	s_nop 0
	global_load_dwordx4 v[86:89], v[88:89], off offset:16
	v_add_u32_e32 v187, 16, v182
	global_load_dword v158, v[160:161], off
	v_add_u32_e32 v185, 32, v182
	v_add_u32_e32 v183, 48, v182
	v_add_u32_e32 v181, 0x80, v182
	v_add_u32_e32 v179, 0x90, v182
	v_add_u32_e32 v177, 0xa0, v182
	v_add_u32_e32 v175, 0xb0, v182
	s_waitcnt vmcnt(0)
	v_fmamk_f32 v158, v158, 0x3a800000, v223
	v_cmp_gt_f32_e32 vcc, s95, v158
	v_mul_f32_e32 v168, 0x4b800000, v158
	s_nop 0
	v_cndmask_b32_e32 v158, v158, v168, vcc
	v_rsq_f32_e32 v158, v158
	s_nop 0
	v_mul_f32_e32 v168, 0x45800000, v158
	v_cndmask_b32_e32 v184, v158, v168, vcc
	global_load_dword v158, v[160:161], off offset:64
	s_waitcnt vmcnt(0)
	v_fmamk_f32 v158, v158, 0x3a800000, v223
	v_cmp_gt_f32_e32 vcc, s95, v158
	v_mul_f32_e32 v168, 0x4b800000, v158
	s_nop 0
	v_cndmask_b32_e32 v158, v158, v168, vcc
	v_rsq_f32_e32 v158, v158
	s_nop 0
	v_mul_f32_e32 v168, 0x45800000, v158
	v_cndmask_b32_e32 v180, v158, v168, vcc
	global_load_dword v158, v[160:161], off offset:128
	s_waitcnt vmcnt(0)
	v_fmamk_f32 v158, v158, 0x3a800000, v223
	v_cmp_gt_f32_e32 vcc, s95, v158
	v_mul_f32_e32 v168, 0x4b800000, v158
	s_nop 0
	v_cndmask_b32_e32 v158, v158, v168, vcc
	v_rsq_f32_e32 v158, v158
	s_nop 0
	v_mul_f32_e32 v168, 0x45800000, v158
	v_cndmask_b32_e32 v178, v158, v168, vcc
	global_load_dword v158, v[160:161], off offset:192
	s_waitcnt vmcnt(0)
	v_fmamk_f32 v158, v158, 0x3a800000, v223
	v_cmp_gt_f32_e32 vcc, s95, v158
	v_mul_f32_e32 v168, 0x4b800000, v158
	s_nop 0
	v_cndmask_b32_e32 v158, v158, v168, vcc
	v_rsq_f32_e32 v158, v158
	s_nop 0
	v_mul_f32_e32 v168, 0x45800000, v158
	v_cndmask_b32_e32 v176, v158, v168, vcc
	global_load_dword v158, v[160:161], off offset:512
	s_waitcnt vmcnt(0)
	v_fmamk_f32 v158, v158, 0x3a800000, v223
	v_cmp_gt_f32_e32 vcc, s95, v158
	v_mul_f32_e32 v168, 0x4b800000, v158
	s_nop 0
	v_cndmask_b32_e32 v158, v158, v168, vcc
	v_rsq_f32_e32 v158, v158
	s_nop 0
	v_mul_f32_e32 v168, 0x45800000, v158
	v_cndmask_b32_e32 v174, v158, v168, vcc
	global_load_dword v158, v[160:161], off offset:576
	s_waitcnt vmcnt(0)
	v_fmamk_f32 v158, v158, 0x3a800000, v223
	v_cmp_gt_f32_e32 vcc, s95, v158
	v_mul_f32_e32 v168, 0x4b800000, v158
	s_nop 0
	v_cndmask_b32_e32 v158, v158, v168, vcc
	v_rsq_f32_e32 v158, v158
	s_nop 0
	v_mul_f32_e32 v168, 0x45800000, v158
	v_cndmask_b32_e32 v172, v158, v168, vcc
	global_load_dword v158, v[160:161], off offset:640
	s_waitcnt vmcnt(0)
	v_fmamk_f32 v158, v158, 0x3a800000, v223
	global_load_dword v160, v[160:161], off offset:704
	v_cmp_gt_f32_e32 vcc, s95, v158
	v_mul_f32_e32 v168, 0x4b800000, v158
	s_waitcnt vmcnt(0)
	v_fmamk_f32 v160, v160, 0x3a800000, v223
	v_cndmask_b32_e32 v158, v158, v168, vcc
	v_rsq_f32_e32 v158, v158
	v_mul_f32_e32 v161, 0x4b800000, v160
	v_mul_f32_e32 v168, 0x45800000, v158
	v_cndmask_b32_e32 v158, v158, v168, vcc
	v_cmp_gt_f32_e32 vcc, s95, v160
	v_and_b32_e32 v168, 56, v186
	s_nop 0
	v_cndmask_b32_e32 v160, v160, v161, vcc
	v_rsq_f32_e32 v160, v160
	s_nop 0
	v_mul_f32_e32 v161, 0x45800000, v160
	v_cndmask_b32_e32 v160, v160, v161, vcc
	v_ashrrev_i32_e32 v161, 6, v186
	v_pk_fma_f32 v[138:139], v[138:139], v[184:185], v[98:99] op_sel_hi:[1,0,1]
	v_pk_fma_f32 v[142:143], v[142:143], v[184:185], v[102:103] op_sel_hi:[1,0,1]
	v_mul_f32_e32 v169, 0xbfb8aa3b, v138
	v_exp_f32_e32 v169, v169
	v_pk_fma_f32 v[140:141], v[140:141], v[184:185], v[100:101] op_sel_hi:[1,0,1]
	v_pk_fma_f32 v[134:135], v[134:135], v[184:185], v[82:83] op_sel_hi:[1,0,1]
	v_pk_fma_f32 v[130:131], v[130:131], v[184:185], v[86:87] op_sel_hi:[1,0,1]
	v_add_f32_e32 v169, 1.0, v169
	v_rcp_f32_e32 v188, v169
	v_mul_f32_e32 v169, 0xbfb8aa3b, v139
	v_exp_f32_e32 v169, v169
	v_pk_fma_f32 v[132:133], v[132:133], v[184:185], v[88:89] op_sel_hi:[1,0,1]
	v_readlane_b32 s14, v254, 27
	v_readlane_b32 s15, v254, 28
	v_add_f32_e32 v169, 1.0, v169
	v_rcp_f32_e32 v189, v169
	s_nop 0
	v_pk_mul_f32 v[138:139], v[138:139], v[188:189]
	s_nop 0
	v_pk_mul_f32 v[138:139], v[142:143], v[138:139]
	v_pk_fma_f32 v[142:143], v[144:145], v[184:185], v[104:105] op_sel_hi:[1,0,1]
	v_mul_f32_e32 v144, 0xbfb8aa3b, v140
	v_mul_f32_e32 v145, 0xbfb8aa3b, v141
	v_exp_f32_e32 v144, v144
	v_exp_f32_e32 v145, v145
	v_add_f32_e32 v144, 1.0, v144
	v_add_f32_e32 v145, 1.0, v145
	v_rcp_f32_e32 v144, v144
	v_rcp_f32_e32 v145, v145
	s_nop 0
	v_pk_mul_f32 v[140:141], v[140:141], v[144:145]
	s_nop 0
	v_pk_mul_f32 v[140:141], v[142:143], v[140:141]
	v_mul_f32_e32 v142, 0xbfb8aa3b, v134
	v_mul_f32_e32 v143, 0xbfb8aa3b, v135
	v_exp_f32_e32 v142, v142
	v_exp_f32_e32 v143, v143
	v_add_f32_e32 v142, 1.0, v142
	v_add_f32_e32 v143, 1.0, v143
	v_rcp_f32_e32 v142, v142
	v_rcp_f32_e32 v143, v143
	s_nop 0
	v_pk_mul_f32 v[134:135], v[134:135], v[142:143]
	s_nop 0
	v_pk_mul_f32 v[130:131], v[130:131], v[134:135]
	v_pk_fma_f32 v[134:135], v[136:137], v[184:185], v[84:85] op_sel_hi:[1,0,1]
	s_nop 0
	v_mul_f32_e32 v136, 0xbfb8aa3b, v134
	v_mul_f32_e32 v137, 0xbfb8aa3b, v135
	v_exp_f32_e32 v136, v136
	v_exp_f32_e32 v137, v137
	v_add_f32_e32 v136, 1.0, v136
	v_add_f32_e32 v137, 1.0, v137
	v_rcp_f32_e32 v136, v136
	v_rcp_f32_e32 v137, v137
	s_nop 0
	v_pk_mul_f32 v[134:135], v[134:135], v[136:137]
	s_nop 0
	v_pk_mul_f32 v[136:137], v[132:133], v[134:135]
	v_cvt_pk_bf16_f32 v134, v130, v131
	v_lshrrev_b32_e32 v130, 8, v182
	v_mad_i32_i24 v130, v130, 44, v161
	v_ashrrev_i32_e32 v131, 31, v130
	v_cvt_pk_bf16_f32 v135, v136, v137
	v_lshlrev_b64 v[130:131], 15, v[130:131]
	v_lshlrev_b32_e32 v136, 7, v182
	v_lshl_add_u64 v[130:131], s[14:15], 0, v[130:131]
	v_and_b32_e32 v136, 0x7f80, v136
	v_mov_b32_e32 v137, v0
	v_lshl_add_u64 v[136:137], v[130:131], 0, v[136:137]
	v_lshlrev_b32_e32 v130, 1, v168
	v_mov_b32_e32 v131, v0
	v_cvt_pk_bf16_f32 v132, v138, v139
	v_cvt_pk_bf16_f32 v133, v140, v141
	v_lshl_add_u64 v[136:137], v[136:137], 0, v[130:131]
	global_store_dwordx4 v[136:137], v[132:135], off sc1
	v_pk_fma_f32 v[126:127], v[126:127], v[180:181], v[98:99] op_sel_hi:[1,0,1]
	v_pk_fma_f32 v[122:123], v[122:123], v[180:181], v[102:103] op_sel_hi:[1,0,1]
	v_mul_f32_e32 v132, 0xbfb8aa3b, v126
	v_mul_f32_e32 v133, 0xbfb8aa3b, v127
	v_exp_f32_e32 v132, v132
	v_exp_f32_e32 v133, v133
	v_pk_fma_f32 v[124:125], v[124:125], v[180:181], v[104:105] op_sel_hi:[1,0,1]
	v_pk_fma_f32 v[118:119], v[118:119], v[180:181], v[82:83] op_sel_hi:[1,0,1]
	v_add_f32_e32 v132, 1.0, v132
	v_add_f32_e32 v133, 1.0, v133
	v_rcp_f32_e32 v132, v132
	v_rcp_f32_e32 v133, v133
	v_pk_fma_f32 v[114:115], v[114:115], v[180:181], v[86:87] op_sel_hi:[1,0,1]
	v_pk_fma_f32 v[116:117], v[116:117], v[180:181], v[88:89] op_sel_hi:[1,0,1]
	v_pk_mul_f32 v[126:127], v[126:127], v[132:133]
	s_nop 0
	v_pk_mul_f32 v[122:123], v[122:123], v[126:127]
	v_pk_fma_f32 v[126:127], v[128:129], v[180:181], v[100:101] op_sel_hi:[1,0,1]
	s_nop 0
	v_mul_f32_e32 v128, 0xbfb8aa3b, v126
	v_mul_f32_e32 v129, 0xbfb8aa3b, v127
	v_exp_f32_e32 v128, v128
	v_exp_f32_e32 v129, v129
	v_add_f32_e32 v128, 1.0, v128
	v_add_f32_e32 v129, 1.0, v129
	v_rcp_f32_e32 v128, v128
	v_rcp_f32_e32 v129, v129
	s_nop 0
	v_pk_mul_f32 v[126:127], v[126:127], v[128:129]
	s_nop 0
	v_pk_mul_f32 v[124:125], v[124:125], v[126:127]
	v_mul_f32_e32 v126, 0xbfb8aa3b, v118
	v_mul_f32_e32 v127, 0xbfb8aa3b, v119
	v_exp_f32_e32 v126, v126
	v_exp_f32_e32 v127, v127
	v_add_f32_e32 v126, 1.0, v126
	v_add_f32_e32 v127, 1.0, v127
	v_rcp_f32_e32 v126, v126
	v_rcp_f32_e32 v127, v127
	s_nop 0
	v_pk_mul_f32 v[118:119], v[118:119], v[126:127]
	s_nop 0
	v_pk_mul_f32 v[118:119], v[114:115], v[118:119]
	v_pk_fma_f32 v[114:115], v[120:121], v[180:181], v[84:85] op_sel_hi:[1,0,1]
	s_nop 0
	v_mul_f32_e32 v120, 0xbfb8aa3b, v114
	v_mul_f32_e32 v121, 0xbfb8aa3b, v115
	v_exp_f32_e32 v120, v120
	v_exp_f32_e32 v121, v121
	v_add_f32_e32 v120, 1.0, v120
	v_add_f32_e32 v121, 1.0, v121
	v_rcp_f32_e32 v120, v120
	v_rcp_f32_e32 v121, v121
	s_nop 0
	v_pk_mul_f32 v[114:115], v[114:115], v[120:121]
	s_nop 0
	v_pk_mul_f32 v[120:121], v[116:117], v[114:115]
	v_cvt_pk_bf16_f32 v116, v118, v119
	v_lshrrev_b32_e32 v118, 8, v187
	v_mad_i32_i24 v118, v118, 44, v161
	v_ashrrev_i32_e32 v119, 31, v118
	v_cvt_pk_bf16_f32 v117, v120, v121
	v_lshlrev_b64 v[118:119], 15, v[118:119]
	v_lshlrev_b32_e32 v120, 7, v187
	v_lshl_add_u64 v[118:119], s[14:15], 0, v[118:119]
	v_and_b32_e32 v120, 0x7f80, v120
	v_mov_b32_e32 v121, v0
	v_lshl_add_u64 v[118:119], v[118:119], 0, v[120:121]
	v_cvt_pk_bf16_f32 v114, v122, v123
	v_cvt_pk_bf16_f32 v115, v124, v125
	v_lshl_add_u64 v[118:119], v[118:119], 0, v[130:131]
	global_store_dwordx4 v[118:119], v[114:117], off sc1
	v_pk_fma_f32 v[110:111], v[110:111], v[178:179], v[98:99] op_sel_hi:[1,0,1]
	v_pk_fma_f32 v[106:107], v[106:107], v[178:179], v[102:103] op_sel_hi:[1,0,1]
	v_mul_f32_e32 v114, 0xbfb8aa3b, v110
	v_mul_f32_e32 v115, 0xbfb8aa3b, v111
	v_exp_f32_e32 v114, v114
	v_exp_f32_e32 v115, v115
	v_pk_fma_f32 v[108:109], v[108:109], v[178:179], v[104:105] op_sel_hi:[1,0,1]
	v_pk_fma_f32 v[94:95], v[94:95], v[178:179], v[82:83] op_sel_hi:[1,0,1]
	v_add_f32_e32 v114, 1.0, v114
	v_add_f32_e32 v115, 1.0, v115
	v_rcp_f32_e32 v114, v114
	v_rcp_f32_e32 v115, v115
	v_pk_fma_f32 v[90:91], v[90:91], v[178:179], v[86:87] op_sel_hi:[1,0,1]
	v_pk_fma_f32 v[92:93], v[92:93], v[178:179], v[88:89] op_sel_hi:[1,0,1]
	v_pk_mul_f32 v[110:111], v[110:111], v[114:115]
	s_nop 0
	v_pk_mul_f32 v[106:107], v[106:107], v[110:111]
	v_pk_fma_f32 v[110:111], v[112:113], v[178:179], v[100:101] op_sel_hi:[1,0,1]
	s_nop 0
	v_mul_f32_e32 v112, 0xbfb8aa3b, v110
	v_mul_f32_e32 v113, 0xbfb8aa3b, v111
	v_exp_f32_e32 v112, v112
	v_exp_f32_e32 v113, v113
	v_add_f32_e32 v112, 1.0, v112
	v_add_f32_e32 v113, 1.0, v113
	v_rcp_f32_e32 v112, v112
	v_rcp_f32_e32 v113, v113
	s_nop 0
	v_pk_mul_f32 v[110:111], v[110:111], v[112:113]
	s_nop 0
	v_pk_mul_f32 v[108:109], v[108:109], v[110:111]
	v_mul_f32_e32 v110, 0xbfb8aa3b, v94
	v_mul_f32_e32 v111, 0xbfb8aa3b, v95
	v_exp_f32_e32 v110, v110
	v_exp_f32_e32 v111, v111
	v_add_f32_e32 v110, 1.0, v110
	v_add_f32_e32 v111, 1.0, v111
	v_rcp_f32_e32 v110, v110
	v_rcp_f32_e32 v111, v111
	s_nop 0
	v_pk_mul_f32 v[94:95], v[94:95], v[110:111]
	s_nop 0
	v_pk_mul_f32 v[94:95], v[90:91], v[94:95]
	v_pk_fma_f32 v[90:91], v[96:97], v[178:179], v[84:85] op_sel_hi:[1,0,1]
	s_nop 0
	v_mul_f32_e32 v96, 0xbfb8aa3b, v90
	v_mul_f32_e32 v97, 0xbfb8aa3b, v91
	v_exp_f32_e32 v96, v96
	v_exp_f32_e32 v97, v97
	v_add_f32_e32 v96, 1.0, v96
	v_add_f32_e32 v97, 1.0, v97
	v_rcp_f32_e32 v96, v96
	v_rcp_f32_e32 v97, v97
	s_nop 0
	v_pk_mul_f32 v[90:91], v[90:91], v[96:97]
	s_nop 0
	v_pk_mul_f32 v[96:97], v[92:93], v[90:91]
	v_cvt_pk_bf16_f32 v92, v94, v95
	v_lshrrev_b32_e32 v94, 8, v185
	v_mad_i32_i24 v94, v94, 44, v161
	v_ashrrev_i32_e32 v95, 31, v94
	v_cvt_pk_bf16_f32 v93, v96, v97
	v_lshlrev_b64 v[94:95], 15, v[94:95]
	v_lshlrev_b32_e32 v96, 7, v185
	v_lshl_add_u64 v[94:95], s[14:15], 0, v[94:95]
	v_and_b32_e32 v96, 0x7f80, v96
	v_mov_b32_e32 v97, v0
	v_lshl_add_u64 v[94:95], v[94:95], 0, v[96:97]
	v_cvt_pk_bf16_f32 v90, v106, v107
	v_cvt_pk_bf16_f32 v91, v108, v109
	v_lshl_add_u64 v[94:95], v[94:95], 0, v[130:131]
	global_store_dwordx4 v[94:95], v[90:93], off sc1
	v_pk_fma_f32 v[78:79], v[78:79], v[176:177], v[98:99] op_sel_hi:[1,0,1]
	v_pk_fma_f32 v[74:75], v[74:75], v[176:177], v[102:103] op_sel_hi:[1,0,1]
	v_mul_f32_e32 v90, 0xbfb8aa3b, v78
	v_mul_f32_e32 v91, 0xbfb8aa3b, v79
	v_exp_f32_e32 v90, v90
	v_exp_f32_e32 v91, v91
	v_pk_fma_f32 v[76:77], v[76:77], v[176:177], v[104:105] op_sel_hi:[1,0,1]
	v_pk_fma_f32 v[70:71], v[70:71], v[176:177], v[82:83] op_sel_hi:[1,0,1]
	v_add_f32_e32 v90, 1.0, v90
	v_add_f32_e32 v91, 1.0, v91
	v_rcp_f32_e32 v90, v90
	v_rcp_f32_e32 v91, v91
	v_pk_fma_f32 v[66:67], v[66:67], v[176:177], v[86:87] op_sel_hi:[1,0,1]
	v_pk_fma_f32 v[68:69], v[68:69], v[176:177], v[88:89] op_sel_hi:[1,0,1]
	v_pk_mul_f32 v[78:79], v[78:79], v[90:91]
	s_nop 0
	v_pk_mul_f32 v[74:75], v[74:75], v[78:79]
	v_pk_fma_f32 v[78:79], v[80:81], v[176:177], v[100:101] op_sel_hi:[1,0,1]
	s_nop 0
	v_mul_f32_e32 v80, 0xbfb8aa3b, v78
	v_mul_f32_e32 v81, 0xbfb8aa3b, v79
	v_exp_f32_e32 v80, v80
	v_exp_f32_e32 v81, v81
	v_add_f32_e32 v80, 1.0, v80
	v_add_f32_e32 v81, 1.0, v81
	v_rcp_f32_e32 v80, v80
	v_rcp_f32_e32 v81, v81
	s_nop 0
	v_pk_mul_f32 v[78:79], v[78:79], v[80:81]
	s_nop 0
	v_pk_mul_f32 v[76:77], v[76:77], v[78:79]
	v_mul_f32_e32 v78, 0xbfb8aa3b, v70
	v_mul_f32_e32 v79, 0xbfb8aa3b, v71
	v_exp_f32_e32 v78, v78
	v_exp_f32_e32 v79, v79
	v_add_f32_e32 v78, 1.0, v78
	v_add_f32_e32 v79, 1.0, v79
	v_rcp_f32_e32 v78, v78
	v_rcp_f32_e32 v79, v79
	s_nop 0
	v_pk_mul_f32 v[70:71], v[70:71], v[78:79]
	s_nop 0
	v_pk_mul_f32 v[70:71], v[66:67], v[70:71]
	v_pk_fma_f32 v[66:67], v[72:73], v[176:177], v[84:85] op_sel_hi:[1,0,1]
	s_nop 0
	v_mul_f32_e32 v72, 0xbfb8aa3b, v66
	v_mul_f32_e32 v73, 0xbfb8aa3b, v67
	v_exp_f32_e32 v72, v72
	v_exp_f32_e32 v73, v73
	v_add_f32_e32 v72, 1.0, v72
	v_add_f32_e32 v73, 1.0, v73
	v_rcp_f32_e32 v72, v72
	v_rcp_f32_e32 v73, v73
	s_nop 0
	v_pk_mul_f32 v[66:67], v[66:67], v[72:73]
	s_nop 0
	v_pk_mul_f32 v[72:73], v[68:69], v[66:67]
	v_cvt_pk_bf16_f32 v68, v70, v71
	v_lshrrev_b32_e32 v70, 8, v183
	v_mad_i32_i24 v70, v70, 44, v161
	v_ashrrev_i32_e32 v71, 31, v70
	v_cvt_pk_bf16_f32 v69, v72, v73
	v_lshlrev_b64 v[70:71], 15, v[70:71]
	v_lshlrev_b32_e32 v72, 7, v183
	v_lshl_add_u64 v[70:71], s[14:15], 0, v[70:71]
	v_and_b32_e32 v72, 0x7f80, v72
	v_mov_b32_e32 v73, v0
	v_lshl_add_u64 v[70:71], v[70:71], 0, v[72:73]
	v_cvt_pk_bf16_f32 v66, v74, v75
	v_cvt_pk_bf16_f32 v67, v76, v77
	v_lshl_add_u64 v[70:71], v[70:71], 0, v[130:131]
	global_store_dwordx4 v[70:71], v[66:69], off sc1
	v_pk_fma_f32 v[62:63], v[62:63], v[174:175], v[98:99] op_sel_hi:[1,0,1]
	v_pk_fma_f32 v[58:59], v[58:59], v[174:175], v[102:103] op_sel_hi:[1,0,1]
	v_mul_f32_e32 v66, 0xbfb8aa3b, v62
	v_mul_f32_e32 v67, 0xbfb8aa3b, v63
	v_exp_f32_e32 v66, v66
	v_exp_f32_e32 v67, v67
	v_pk_fma_f32 v[60:61], v[60:61], v[174:175], v[104:105] op_sel_hi:[1,0,1]
	v_pk_fma_f32 v[54:55], v[54:55], v[174:175], v[82:83] op_sel_hi:[1,0,1]
	v_add_f32_e32 v66, 1.0, v66
	v_add_f32_e32 v67, 1.0, v67
	v_rcp_f32_e32 v66, v66
	v_rcp_f32_e32 v67, v67
	v_pk_fma_f32 v[50:51], v[50:51], v[174:175], v[86:87] op_sel_hi:[1,0,1]
	v_pk_fma_f32 v[52:53], v[52:53], v[174:175], v[88:89] op_sel_hi:[1,0,1]
	v_pk_mul_f32 v[62:63], v[62:63], v[66:67]
	s_nop 0
	v_pk_mul_f32 v[58:59], v[58:59], v[62:63]
	v_pk_fma_f32 v[62:63], v[64:65], v[174:175], v[100:101] op_sel_hi:[1,0,1]
	s_nop 0
	v_mul_f32_e32 v64, 0xbfb8aa3b, v62
	v_mul_f32_e32 v65, 0xbfb8aa3b, v63
	v_exp_f32_e32 v64, v64
	v_exp_f32_e32 v65, v65
	v_add_f32_e32 v64, 1.0, v64
	v_add_f32_e32 v65, 1.0, v65
	v_rcp_f32_e32 v64, v64
	v_rcp_f32_e32 v65, v65
	s_nop 0
	v_pk_mul_f32 v[62:63], v[62:63], v[64:65]
	s_nop 0
	v_pk_mul_f32 v[60:61], v[60:61], v[62:63]
	v_mul_f32_e32 v62, 0xbfb8aa3b, v54
	v_mul_f32_e32 v63, 0xbfb8aa3b, v55
	v_exp_f32_e32 v62, v62
	v_exp_f32_e32 v63, v63
	v_add_f32_e32 v62, 1.0, v62
	v_add_f32_e32 v63, 1.0, v63
	v_rcp_f32_e32 v62, v62
	v_rcp_f32_e32 v63, v63
	s_nop 0
	v_pk_mul_f32 v[54:55], v[54:55], v[62:63]
	s_nop 0
	v_pk_mul_f32 v[54:55], v[50:51], v[54:55]
	v_pk_fma_f32 v[50:51], v[56:57], v[174:175], v[84:85] op_sel_hi:[1,0,1]
	s_nop 0
	v_mul_f32_e32 v56, 0xbfb8aa3b, v50
	v_mul_f32_e32 v57, 0xbfb8aa3b, v51
	v_exp_f32_e32 v56, v56
	v_exp_f32_e32 v57, v57
	v_add_f32_e32 v56, 1.0, v56
	v_add_f32_e32 v57, 1.0, v57
	v_rcp_f32_e32 v56, v56
	v_rcp_f32_e32 v57, v57
	s_nop 0
	v_pk_mul_f32 v[50:51], v[50:51], v[56:57]
	s_nop 0
	v_pk_mul_f32 v[56:57], v[52:53], v[50:51]
	v_cvt_pk_bf16_f32 v52, v54, v55
	v_lshrrev_b32_e32 v54, 8, v181
	v_mad_i32_i24 v54, v54, 44, v161
	v_ashrrev_i32_e32 v55, 31, v54
	v_cvt_pk_bf16_f32 v53, v56, v57
	v_lshlrev_b64 v[54:55], 15, v[54:55]
	v_lshlrev_b32_e32 v56, 7, v181
	v_lshl_add_u64 v[54:55], s[14:15], 0, v[54:55]
	v_and_b32_e32 v56, 0x7f80, v56
	v_mov_b32_e32 v57, v0
	v_lshl_add_u64 v[54:55], v[54:55], 0, v[56:57]
	v_cvt_pk_bf16_f32 v50, v58, v59
	v_cvt_pk_bf16_f32 v51, v60, v61
	v_lshl_add_u64 v[54:55], v[54:55], 0, v[130:131]
	global_store_dwordx4 v[54:55], v[50:53], off sc1
	v_pk_fma_f32 v[46:47], v[46:47], v[172:173], v[98:99] op_sel_hi:[1,0,1]
	v_pk_fma_f32 v[42:43], v[42:43], v[172:173], v[102:103] op_sel_hi:[1,0,1]
	v_mul_f32_e32 v50, 0xbfb8aa3b, v46
	v_mul_f32_e32 v51, 0xbfb8aa3b, v47
	v_exp_f32_e32 v50, v50
	v_exp_f32_e32 v51, v51
	v_pk_fma_f32 v[44:45], v[44:45], v[172:173], v[104:105] op_sel_hi:[1,0,1]
	v_pk_fma_f32 v[38:39], v[38:39], v[172:173], v[82:83] op_sel_hi:[1,0,1]
	v_add_f32_e32 v50, 1.0, v50
	v_add_f32_e32 v51, 1.0, v51
	v_rcp_f32_e32 v50, v50
	v_rcp_f32_e32 v51, v51
	v_pk_fma_f32 v[34:35], v[34:35], v[172:173], v[86:87] op_sel_hi:[1,0,1]
	v_pk_fma_f32 v[36:37], v[36:37], v[172:173], v[88:89] op_sel_hi:[1,0,1]
	v_pk_mul_f32 v[46:47], v[46:47], v[50:51]
	s_nop 0
	v_pk_mul_f32 v[42:43], v[42:43], v[46:47]
	v_pk_fma_f32 v[46:47], v[48:49], v[172:173], v[100:101] op_sel_hi:[1,0,1]
	s_nop 0
	v_mul_f32_e32 v48, 0xbfb8aa3b, v46
	v_mul_f32_e32 v49, 0xbfb8aa3b, v47
	v_exp_f32_e32 v48, v48
	v_exp_f32_e32 v49, v49
	v_add_f32_e32 v48, 1.0, v48
	v_add_f32_e32 v49, 1.0, v49
	v_rcp_f32_e32 v48, v48
	v_rcp_f32_e32 v49, v49
	s_nop 0
	v_pk_mul_f32 v[46:47], v[46:47], v[48:49]
	s_nop 0
	v_pk_mul_f32 v[44:45], v[44:45], v[46:47]
	v_mul_f32_e32 v46, 0xbfb8aa3b, v38
	v_mul_f32_e32 v47, 0xbfb8aa3b, v39
	v_exp_f32_e32 v46, v46
	v_exp_f32_e32 v47, v47
	v_add_f32_e32 v46, 1.0, v46
	v_add_f32_e32 v47, 1.0, v47
	v_rcp_f32_e32 v46, v46
	v_rcp_f32_e32 v47, v47
	s_nop 0
	v_pk_mul_f32 v[38:39], v[38:39], v[46:47]
	s_nop 0
	v_pk_mul_f32 v[38:39], v[34:35], v[38:39]
	v_pk_fma_f32 v[34:35], v[40:41], v[172:173], v[84:85] op_sel_hi:[1,0,1]
	s_nop 0
	v_mul_f32_e32 v40, 0xbfb8aa3b, v34
	v_mul_f32_e32 v41, 0xbfb8aa3b, v35
	v_exp_f32_e32 v40, v40
	v_exp_f32_e32 v41, v41
	v_add_f32_e32 v40, 1.0, v40
	v_add_f32_e32 v41, 1.0, v41
	v_rcp_f32_e32 v40, v40
	v_rcp_f32_e32 v41, v41
	s_nop 0
	v_pk_mul_f32 v[34:35], v[34:35], v[40:41]
	s_nop 0
	v_pk_mul_f32 v[40:41], v[36:37], v[34:35]
	v_cvt_pk_bf16_f32 v36, v38, v39
	v_lshrrev_b32_e32 v38, 8, v179
	v_mad_i32_i24 v38, v38, 44, v161
	v_ashrrev_i32_e32 v39, 31, v38
	v_cvt_pk_bf16_f32 v37, v40, v41
	v_lshlrev_b64 v[38:39], 15, v[38:39]
	v_lshlrev_b32_e32 v40, 7, v179
	v_lshl_add_u64 v[38:39], s[14:15], 0, v[38:39]
	v_and_b32_e32 v40, 0x7f80, v40
	v_mov_b32_e32 v41, v0
	v_lshl_add_u64 v[38:39], v[38:39], 0, v[40:41]
	v_cvt_pk_bf16_f32 v34, v42, v43
	v_cvt_pk_bf16_f32 v35, v44, v45
	v_lshl_add_u64 v[38:39], v[38:39], 0, v[130:131]
	global_store_dwordx4 v[38:39], v[34:37], off sc1
	v_pk_fma_f32 v[30:31], v[30:31], v[158:159], v[98:99] op_sel_hi:[1,0,1]
	v_pk_fma_f32 v[26:27], v[26:27], v[158:159], v[102:103] op_sel_hi:[1,0,1]
	v_mul_f32_e32 v34, 0xbfb8aa3b, v30
	v_mul_f32_e32 v35, 0xbfb8aa3b, v31
	v_exp_f32_e32 v34, v34
	v_exp_f32_e32 v35, v35
	v_pk_fma_f32 v[28:29], v[28:29], v[158:159], v[104:105] op_sel_hi:[1,0,1]
	v_pk_fma_f32 v[22:23], v[22:23], v[158:159], v[82:83] op_sel_hi:[1,0,1]
	v_add_f32_e32 v34, 1.0, v34
	v_add_f32_e32 v35, 1.0, v35
	v_rcp_f32_e32 v34, v34
	v_rcp_f32_e32 v35, v35
	v_pk_fma_f32 v[18:19], v[18:19], v[158:159], v[86:87] op_sel_hi:[1,0,1]
	v_pk_fma_f32 v[20:21], v[20:21], v[158:159], v[88:89] op_sel_hi:[1,0,1]
	v_pk_mul_f32 v[30:31], v[30:31], v[34:35]
	s_nop 0
	v_pk_mul_f32 v[26:27], v[26:27], v[30:31]
	v_pk_fma_f32 v[30:31], v[32:33], v[158:159], v[100:101] op_sel_hi:[1,0,1]
	s_nop 0
	v_mul_f32_e32 v32, 0xbfb8aa3b, v30
	v_mul_f32_e32 v33, 0xbfb8aa3b, v31
	v_exp_f32_e32 v32, v32
	v_exp_f32_e32 v33, v33
	v_add_f32_e32 v32, 1.0, v32
	v_add_f32_e32 v33, 1.0, v33
	v_rcp_f32_e32 v32, v32
	v_rcp_f32_e32 v33, v33
	s_nop 0
	v_pk_mul_f32 v[30:31], v[30:31], v[32:33]
	s_nop 0
	v_pk_mul_f32 v[28:29], v[28:29], v[30:31]
	v_mul_f32_e32 v30, 0xbfb8aa3b, v22
	v_mul_f32_e32 v31, 0xbfb8aa3b, v23
	v_exp_f32_e32 v30, v30
	v_exp_f32_e32 v31, v31
	v_add_f32_e32 v30, 1.0, v30
	v_add_f32_e32 v31, 1.0, v31
	v_rcp_f32_e32 v30, v30
	v_rcp_f32_e32 v31, v31
	s_nop 0
	v_pk_mul_f32 v[22:23], v[22:23], v[30:31]
	s_nop 0
	v_pk_mul_f32 v[22:23], v[18:19], v[22:23]
	v_pk_fma_f32 v[18:19], v[24:25], v[158:159], v[84:85] op_sel_hi:[1,0,1]
	s_nop 0
	v_mul_f32_e32 v24, 0xbfb8aa3b, v18
	v_mul_f32_e32 v25, 0xbfb8aa3b, v19
	v_exp_f32_e32 v24, v24
	v_exp_f32_e32 v25, v25
	v_add_f32_e32 v24, 1.0, v24
	v_add_f32_e32 v25, 1.0, v25
	v_rcp_f32_e32 v24, v24
	v_rcp_f32_e32 v25, v25
	s_nop 0
	v_pk_mul_f32 v[18:19], v[18:19], v[24:25]
	s_nop 0
	v_pk_mul_f32 v[24:25], v[20:21], v[18:19]
	v_cvt_pk_bf16_f32 v20, v22, v23
	v_lshrrev_b32_e32 v22, 8, v177
	v_mad_i32_i24 v22, v22, 44, v161
	v_ashrrev_i32_e32 v23, 31, v22
	v_cvt_pk_bf16_f32 v21, v24, v25
	v_lshlrev_b64 v[22:23], 15, v[22:23]
	v_lshlrev_b32_e32 v24, 7, v177
	v_lshl_add_u64 v[22:23], s[14:15], 0, v[22:23]
	v_and_b32_e32 v24, 0x7f80, v24
	v_mov_b32_e32 v25, v0
	v_lshl_add_u64 v[22:23], v[22:23], 0, v[24:25]
	v_cvt_pk_bf16_f32 v18, v26, v27
	v_cvt_pk_bf16_f32 v19, v28, v29
	v_lshl_add_u64 v[22:23], v[22:23], 0, v[130:131]
	global_store_dwordx4 v[22:23], v[18:21], off sc1
	v_pk_fma_f32 v[14:15], v[14:15], v[160:161], v[98:99] op_sel_hi:[1,0,1]
	v_pk_fma_f32 v[10:11], v[10:11], v[160:161], v[102:103] op_sel_hi:[1,0,1]
	v_mul_f32_e32 v18, 0xbfb8aa3b, v14
	v_mul_f32_e32 v19, 0xbfb8aa3b, v15
	v_exp_f32_e32 v18, v18
	v_exp_f32_e32 v19, v19
	v_pk_fma_f32 v[12:13], v[12:13], v[160:161], v[104:105] op_sel_hi:[1,0,1]
	v_pk_fma_f32 v[6:7], v[6:7], v[160:161], v[82:83] op_sel_hi:[1,0,1]
	v_add_f32_e32 v18, 1.0, v18
	v_add_f32_e32 v19, 1.0, v19
	v_rcp_f32_e32 v18, v18
	v_rcp_f32_e32 v19, v19
	v_pk_fma_f32 v[2:3], v[2:3], v[160:161], v[86:87] op_sel_hi:[1,0,1]
	v_pk_fma_f32 v[4:5], v[4:5], v[160:161], v[88:89] op_sel_hi:[1,0,1]
	s_and_b64 vcc, exec, s[36:37]
	v_pk_mul_f32 v[14:15], v[14:15], v[18:19]
	s_mov_b32 s42, s4
	v_pk_mul_f32 v[10:11], v[10:11], v[14:15]
	v_pk_fma_f32 v[14:15], v[16:17], v[160:161], v[100:101] op_sel_hi:[1,0,1]
	s_mov_b32 s12, s6
	v_mul_f32_e32 v16, 0xbfb8aa3b, v14
	v_mul_f32_e32 v17, 0xbfb8aa3b, v15
	v_exp_f32_e32 v16, v16
	v_exp_f32_e32 v17, v17
	s_mov_b64 s[16:17], s[10:11]
	v_add_f32_e32 v16, 1.0, v16
	v_add_f32_e32 v17, 1.0, v17
	v_rcp_f32_e32 v16, v16
	v_rcp_f32_e32 v17, v17
	s_nop 0
	v_pk_mul_f32 v[14:15], v[14:15], v[16:17]
	s_nop 0
	v_pk_mul_f32 v[12:13], v[12:13], v[14:15]
	v_mul_f32_e32 v14, 0xbfb8aa3b, v6
	v_mul_f32_e32 v15, 0xbfb8aa3b, v7
	v_exp_f32_e32 v14, v14
	v_exp_f32_e32 v15, v15
	v_add_f32_e32 v14, 1.0, v14
	v_add_f32_e32 v15, 1.0, v15
	v_rcp_f32_e32 v14, v14
	v_rcp_f32_e32 v15, v15
	s_nop 0
	v_pk_mul_f32 v[6:7], v[6:7], v[14:15]
	s_nop 0
	v_pk_mul_f32 v[6:7], v[2:3], v[6:7]
	v_pk_fma_f32 v[2:3], v[8:9], v[160:161], v[84:85] op_sel_hi:[1,0,1]
	s_nop 0
	v_mul_f32_e32 v8, 0xbfb8aa3b, v2
	v_mul_f32_e32 v9, 0xbfb8aa3b, v3
	v_exp_f32_e32 v8, v8
	v_exp_f32_e32 v9, v9
	v_add_f32_e32 v8, 1.0, v8
	v_add_f32_e32 v9, 1.0, v9
	v_rcp_f32_e32 v8, v8
	v_rcp_f32_e32 v9, v9
	s_nop 0
	v_pk_mul_f32 v[2:3], v[2:3], v[8:9]
	s_nop 0
	v_pk_mul_f32 v[8:9], v[4:5], v[2:3]
	v_cvt_pk_bf16_f32 v4, v6, v7
	v_lshrrev_b32_e32 v6, 8, v175
	v_mad_i32_i24 v6, v6, 44, v161
	v_ashrrev_i32_e32 v7, 31, v6
	v_cvt_pk_bf16_f32 v5, v8, v9
	v_lshlrev_b64 v[6:7], 15, v[6:7]
	v_lshlrev_b32_e32 v8, 7, v175
	v_lshl_add_u64 v[6:7], s[14:15], 0, v[6:7]
	v_and_b32_e32 v8, 0x7f80, v8
	v_mov_b32_e32 v9, v0
	v_lshl_add_u64 v[6:7], v[6:7], 0, v[8:9]
	v_cvt_pk_bf16_f32 v2, v10, v11
	v_cvt_pk_bf16_f32 v3, v12, v13
	v_lshl_add_u64 v[6:7], v[6:7], 0, v[130:131]
	s_mov_b64 s[14:15], s[8:9]
	global_store_dwordx4 v[6:7], v[2:5], off sc1
	s_cbranch_vccnz .LBB0_625

.LBB0_869:
	s_lshl_b32 s3, s10, 8
	v_mov_b32_e32 v82, v159
	v_mov_b32_e32 v83, v1
	s_add_i32 s3, s3, s27
	v_readlane_b32 s12, v254, 33
	v_add_u32_e32 v182, s3, v82
	s_lshl_b32 s3, s38, 7
	s_or_b32 s3, s3, s28
	v_lshl_add_u32 v186, v83, 3, s3
	s_ashr_i32 s3, s10, 5
	s_mul_hi_i32 s5, s3, 0x5800
	s_mulk_i32 s3, 0x5800
	v_readlane_b32 s13, v254, 34
	s_add_u32 s12, s12, s3
	s_addc_u32 s13, s13, s5
	v_ashrrev_i32_e32 v187, 31, v186
	v_lshl_add_u64 v[86:87], v[186:187], 2, s[12:13]
	s_mov_b64 s[12:13], 0x2c00
	v_lshl_add_u64 v[88:89], v[86:87], 0, s[12:13]
	s_movk_i32 s3, 0x2000
	v_readlane_b32 s12, v254, 31
	global_load_dwordx4 v[82:85], v[86:87], off offset:16
	global_load_dwordx4 v[98:101], v[86:87], off
	v_add_co_u32_e32 v86, vcc, s3, v86
	v_ashrrev_i32_e32 v183, 31, v182
	v_readlane_b32 s13, v254, 32
	v_addc_co_u32_e32 v87, vcc, 0, v87, vcc
	s_nop 0
	v_lshl_add_u64 v[160:161], v[182:183], 2, s[12:13]
	global_load_dwordx4 v[102:105], v[86:87], off offset:3072
	s_nop 0
	global_load_dwordx4 v[86:89], v[88:89], off offset:16
	v_add_u32_e32 v187, 16, v182
	global_load_dword v158, v[160:161], off
	v_add_u32_e32 v185, 32, v182
	v_add_u32_e32 v183, 48, v182
	v_add_u32_e32 v181, 0x80, v182
	v_add_u32_e32 v179, 0x90, v182
	v_add_u32_e32 v177, 0xa0, v182
	v_add_u32_e32 v175, 0xb0, v182
	s_waitcnt vmcnt(0)
	v_fmamk_f32 v158, v158, 0x3a800000, v223
	v_cmp_gt_f32_e32 vcc, s95, v158
	v_mul_f32_e32 v168, 0x4b800000, v158
	s_nop 0
	v_cndmask_b32_e32 v158, v158, v168, vcc
	v_rsq_f32_e32 v158, v158
	s_nop 0
	v_mul_f32_e32 v168, 0x45800000, v158
	v_cndmask_b32_e32 v184, v158, v168, vcc
	global_load_dword v158, v[160:161], off offset:64
	s_waitcnt vmcnt(0)
	v_fmamk_f32 v158, v158, 0x3a800000, v223
	v_cmp_gt_f32_e32 vcc, s95, v158
	v_mul_f32_e32 v168, 0x4b800000, v158
	s_nop 0
	v_cndmask_b32_e32 v158, v158, v168, vcc
	v_rsq_f32_e32 v158, v158
	s_nop 0
	v_mul_f32_e32 v168, 0x45800000, v158
	v_cndmask_b32_e32 v180, v158, v168, vcc
	global_load_dword v158, v[160:161], off offset:128
	s_waitcnt vmcnt(0)
	v_fmamk_f32 v158, v158, 0x3a800000, v223
	v_cmp_gt_f32_e32 vcc, s95, v158
	v_mul_f32_e32 v168, 0x4b800000, v158
	s_nop 0
	v_cndmask_b32_e32 v158, v158, v168, vcc
	v_rsq_f32_e32 v158, v158
	s_nop 0
	v_mul_f32_e32 v168, 0x45800000, v158
	v_cndmask_b32_e32 v178, v158, v168, vcc
	global_load_dword v158, v[160:161], off offset:192
	s_waitcnt vmcnt(0)
	v_fmamk_f32 v158, v158, 0x3a800000, v223
	v_cmp_gt_f32_e32 vcc, s95, v158
	v_mul_f32_e32 v168, 0x4b800000, v158
	s_nop 0
	v_cndmask_b32_e32 v158, v158, v168, vcc
	v_rsq_f32_e32 v158, v158
	s_nop 0
	v_mul_f32_e32 v168, 0x45800000, v158
	v_cndmask_b32_e32 v176, v158, v168, vcc
	global_load_dword v158, v[160:161], off offset:512
	s_waitcnt vmcnt(0)
	v_fmamk_f32 v158, v158, 0x3a800000, v223
	v_cmp_gt_f32_e32 vcc, s95, v158
	v_mul_f32_e32 v168, 0x4b800000, v158
	s_nop 0
	v_cndmask_b32_e32 v158, v158, v168, vcc
	v_rsq_f32_e32 v158, v158
	s_nop 0
	v_mul_f32_e32 v168, 0x45800000, v158
	v_cndmask_b32_e32 v174, v158, v168, vcc
	global_load_dword v158, v[160:161], off offset:576
	s_waitcnt vmcnt(0)
	v_fmamk_f32 v158, v158, 0x3a800000, v223
	v_cmp_gt_f32_e32 vcc, s95, v158
	v_mul_f32_e32 v168, 0x4b800000, v158
	s_nop 0
	v_cndmask_b32_e32 v158, v158, v168, vcc
	v_rsq_f32_e32 v158, v158
	s_nop 0
	v_mul_f32_e32 v168, 0x45800000, v158
	v_cndmask_b32_e32 v172, v158, v168, vcc
	global_load_dword v158, v[160:161], off offset:640
	s_waitcnt vmcnt(0)
	v_fmamk_f32 v158, v158, 0x3a800000, v223
	global_load_dword v160, v[160:161], off offset:704
	v_cmp_gt_f32_e32 vcc, s95, v158
	v_mul_f32_e32 v168, 0x4b800000, v158
	s_waitcnt vmcnt(0)
	v_fmamk_f32 v160, v160, 0x3a800000, v223
	v_cndmask_b32_e32 v158, v158, v168, vcc
	v_rsq_f32_e32 v158, v158
	v_mul_f32_e32 v161, 0x4b800000, v160
	v_mul_f32_e32 v168, 0x45800000, v158
	v_cndmask_b32_e32 v158, v158, v168, vcc
	v_cmp_gt_f32_e32 vcc, s95, v160
	v_and_b32_e32 v168, 56, v186
	s_nop 0
	v_cndmask_b32_e32 v160, v160, v161, vcc
	v_rsq_f32_e32 v160, v160
	s_nop 0
	v_mul_f32_e32 v161, 0x45800000, v160
	v_cndmask_b32_e32 v160, v160, v161, vcc
	v_ashrrev_i32_e32 v161, 6, v186
	v_pk_fma_f32 v[138:139], v[138:139], v[184:185], v[98:99] op_sel_hi:[1,0,1]
	v_pk_fma_f32 v[142:143], v[142:143], v[184:185], v[102:103] op_sel_hi:[1,0,1]
	v_mul_f32_e32 v169, 0xbfb8aa3b, v138
	v_exp_f32_e32 v169, v169
	v_pk_fma_f32 v[140:141], v[140:141], v[184:185], v[100:101] op_sel_hi:[1,0,1]
	v_pk_fma_f32 v[134:135], v[134:135], v[184:185], v[82:83] op_sel_hi:[1,0,1]
	v_pk_fma_f32 v[130:131], v[130:131], v[184:185], v[86:87] op_sel_hi:[1,0,1]
	v_add_f32_e32 v169, 1.0, v169
	v_rcp_f32_e32 v188, v169
	v_mul_f32_e32 v169, 0xbfb8aa3b, v139
	v_exp_f32_e32 v169, v169
	v_pk_fma_f32 v[132:133], v[132:133], v[184:185], v[88:89] op_sel_hi:[1,0,1]
	v_readlane_b32 s12, v254, 27
	v_readlane_b32 s13, v254, 28
	v_add_f32_e32 v169, 1.0, v169
	v_rcp_f32_e32 v189, v169
	s_nop 0
	v_pk_mul_f32 v[138:139], v[138:139], v[188:189]
	s_nop 0
	v_pk_mul_f32 v[138:139], v[142:143], v[138:139]
	v_pk_fma_f32 v[142:143], v[144:145], v[184:185], v[104:105] op_sel_hi:[1,0,1]
	v_mul_f32_e32 v144, 0xbfb8aa3b, v140
	v_mul_f32_e32 v145, 0xbfb8aa3b, v141
	v_exp_f32_e32 v144, v144
	v_exp_f32_e32 v145, v145
	v_add_f32_e32 v144, 1.0, v144
	v_add_f32_e32 v145, 1.0, v145
	v_rcp_f32_e32 v144, v144
	v_rcp_f32_e32 v145, v145
	s_nop 0
	v_pk_mul_f32 v[140:141], v[140:141], v[144:145]
	s_nop 0
	v_pk_mul_f32 v[140:141], v[142:143], v[140:141]
	v_mul_f32_e32 v142, 0xbfb8aa3b, v134
	v_mul_f32_e32 v143, 0xbfb8aa3b, v135
	v_exp_f32_e32 v142, v142
	v_exp_f32_e32 v143, v143
	v_add_f32_e32 v142, 1.0, v142
	v_add_f32_e32 v143, 1.0, v143
	v_rcp_f32_e32 v142, v142
	v_rcp_f32_e32 v143, v143
	s_nop 0
	v_pk_mul_f32 v[134:135], v[134:135], v[142:143]
	s_nop 0
	v_pk_mul_f32 v[130:131], v[130:131], v[134:135]
	v_pk_fma_f32 v[134:135], v[136:137], v[184:185], v[84:85] op_sel_hi:[1,0,1]
	s_nop 0
	v_mul_f32_e32 v136, 0xbfb8aa3b, v134
	v_mul_f32_e32 v137, 0xbfb8aa3b, v135
	v_exp_f32_e32 v136, v136
	v_exp_f32_e32 v137, v137
	v_add_f32_e32 v136, 1.0, v136
	v_add_f32_e32 v137, 1.0, v137
	v_rcp_f32_e32 v136, v136
	v_rcp_f32_e32 v137, v137
	s_nop 0
	v_pk_mul_f32 v[134:135], v[134:135], v[136:137]
	s_nop 0
	v_pk_mul_f32 v[136:137], v[132:133], v[134:135]
	v_cvt_pk_bf16_f32 v134, v130, v131
	v_lshrrev_b32_e32 v130, 8, v182
	v_mad_i32_i24 v130, v130, 44, v161
	v_ashrrev_i32_e32 v131, 31, v130
	v_cvt_pk_bf16_f32 v135, v136, v137
	v_lshlrev_b64 v[130:131], 15, v[130:131]
	v_lshlrev_b32_e32 v136, 7, v182
	v_lshl_add_u64 v[130:131], s[12:13], 0, v[130:131]
	v_and_b32_e32 v136, 0x7f80, v136
	v_mov_b32_e32 v137, v0
	v_lshl_add_u64 v[136:137], v[130:131], 0, v[136:137]
	v_lshlrev_b32_e32 v130, 1, v168
	v_mov_b32_e32 v131, v0
	v_cvt_pk_bf16_f32 v132, v138, v139
	v_cvt_pk_bf16_f32 v133, v140, v141
	v_lshl_add_u64 v[136:137], v[136:137], 0, v[130:131]
	global_store_dwordx4 v[136:137], v[132:135], off sc1
	v_pk_fma_f32 v[126:127], v[126:127], v[180:181], v[98:99] op_sel_hi:[1,0,1]
	v_pk_fma_f32 v[122:123], v[122:123], v[180:181], v[102:103] op_sel_hi:[1,0,1]
	v_mul_f32_e32 v132, 0xbfb8aa3b, v126
	v_mul_f32_e32 v133, 0xbfb8aa3b, v127
	v_exp_f32_e32 v132, v132
	v_exp_f32_e32 v133, v133
	v_pk_fma_f32 v[124:125], v[124:125], v[180:181], v[104:105] op_sel_hi:[1,0,1]
	v_pk_fma_f32 v[118:119], v[118:119], v[180:181], v[82:83] op_sel_hi:[1,0,1]
	v_add_f32_e32 v132, 1.0, v132
	v_add_f32_e32 v133, 1.0, v133
	v_rcp_f32_e32 v132, v132
	v_rcp_f32_e32 v133, v133
	v_pk_fma_f32 v[114:115], v[114:115], v[180:181], v[86:87] op_sel_hi:[1,0,1]
	v_pk_fma_f32 v[116:117], v[116:117], v[180:181], v[88:89] op_sel_hi:[1,0,1]
	v_pk_mul_f32 v[126:127], v[126:127], v[132:133]
	s_nop 0
	v_pk_mul_f32 v[122:123], v[122:123], v[126:127]
	v_pk_fma_f32 v[126:127], v[128:129], v[180:181], v[100:101] op_sel_hi:[1,0,1]
	s_nop 0
	v_mul_f32_e32 v128, 0xbfb8aa3b, v126
	v_mul_f32_e32 v129, 0xbfb8aa3b, v127
	v_exp_f32_e32 v128, v128
	v_exp_f32_e32 v129, v129
	v_add_f32_e32 v128, 1.0, v128
	v_add_f32_e32 v129, 1.0, v129
	v_rcp_f32_e32 v128, v128
	v_rcp_f32_e32 v129, v129
	s_nop 0
	v_pk_mul_f32 v[126:127], v[126:127], v[128:129]
	s_nop 0
	v_pk_mul_f32 v[124:125], v[124:125], v[126:127]
	v_mul_f32_e32 v126, 0xbfb8aa3b, v118
	v_mul_f32_e32 v127, 0xbfb8aa3b, v119
	v_exp_f32_e32 v126, v126
	v_exp_f32_e32 v127, v127
	v_add_f32_e32 v126, 1.0, v126
	v_add_f32_e32 v127, 1.0, v127
	v_rcp_f32_e32 v126, v126
	v_rcp_f32_e32 v127, v127
	s_nop 0
	v_pk_mul_f32 v[118:119], v[118:119], v[126:127]
	s_nop 0
	v_pk_mul_f32 v[118:119], v[114:115], v[118:119]
	v_pk_fma_f32 v[114:115], v[120:121], v[180:181], v[84:85] op_sel_hi:[1,0,1]
	s_nop 0
	v_mul_f32_e32 v120, 0xbfb8aa3b, v114
	v_mul_f32_e32 v121, 0xbfb8aa3b, v115
	v_exp_f32_e32 v120, v120
	v_exp_f32_e32 v121, v121
	v_add_f32_e32 v120, 1.0, v120
	v_add_f32_e32 v121, 1.0, v121
	v_rcp_f32_e32 v120, v120
	v_rcp_f32_e32 v121, v121
	s_nop 0
	v_pk_mul_f32 v[114:115], v[114:115], v[120:121]
	s_nop 0
	v_pk_mul_f32 v[120:121], v[116:117], v[114:115]
	v_cvt_pk_bf16_f32 v116, v118, v119
	v_lshrrev_b32_e32 v118, 8, v187
	v_mad_i32_i24 v118, v118, 44, v161
	v_ashrrev_i32_e32 v119, 31, v118
	v_cvt_pk_bf16_f32 v117, v120, v121
	v_lshlrev_b64 v[118:119], 15, v[118:119]
	v_lshlrev_b32_e32 v120, 7, v187
	v_lshl_add_u64 v[118:119], s[12:13], 0, v[118:119]
	v_and_b32_e32 v120, 0x7f80, v120
	v_mov_b32_e32 v121, v0
	v_lshl_add_u64 v[118:119], v[118:119], 0, v[120:121]
	v_cvt_pk_bf16_f32 v114, v122, v123
	v_cvt_pk_bf16_f32 v115, v124, v125
	v_lshl_add_u64 v[118:119], v[118:119], 0, v[130:131]
	global_store_dwordx4 v[118:119], v[114:117], off sc1
	v_pk_fma_f32 v[110:111], v[110:111], v[178:179], v[98:99] op_sel_hi:[1,0,1]
	v_pk_fma_f32 v[106:107], v[106:107], v[178:179], v[102:103] op_sel_hi:[1,0,1]
	v_mul_f32_e32 v114, 0xbfb8aa3b, v110
	v_mul_f32_e32 v115, 0xbfb8aa3b, v111
	v_exp_f32_e32 v114, v114
	v_exp_f32_e32 v115, v115
	v_pk_fma_f32 v[108:109], v[108:109], v[178:179], v[104:105] op_sel_hi:[1,0,1]
	v_pk_fma_f32 v[94:95], v[94:95], v[178:179], v[82:83] op_sel_hi:[1,0,1]
	v_add_f32_e32 v114, 1.0, v114
	v_add_f32_e32 v115, 1.0, v115
	v_rcp_f32_e32 v114, v114
	v_rcp_f32_e32 v115, v115
	v_pk_fma_f32 v[90:91], v[90:91], v[178:179], v[86:87] op_sel_hi:[1,0,1]
	v_pk_fma_f32 v[92:93], v[92:93], v[178:179], v[88:89] op_sel_hi:[1,0,1]
	v_pk_mul_f32 v[110:111], v[110:111], v[114:115]
	s_nop 0
	v_pk_mul_f32 v[106:107], v[106:107], v[110:111]
	v_pk_fma_f32 v[110:111], v[112:113], v[178:179], v[100:101] op_sel_hi:[1,0,1]
	s_nop 0
	v_mul_f32_e32 v112, 0xbfb8aa3b, v110
	v_mul_f32_e32 v113, 0xbfb8aa3b, v111
	v_exp_f32_e32 v112, v112
	v_exp_f32_e32 v113, v113
	v_add_f32_e32 v112, 1.0, v112
	v_add_f32_e32 v113, 1.0, v113
	v_rcp_f32_e32 v112, v112
	v_rcp_f32_e32 v113, v113
	s_nop 0
	v_pk_mul_f32 v[110:111], v[110:111], v[112:113]
	s_nop 0
	v_pk_mul_f32 v[108:109], v[108:109], v[110:111]
	v_mul_f32_e32 v110, 0xbfb8aa3b, v94
	v_mul_f32_e32 v111, 0xbfb8aa3b, v95
	v_exp_f32_e32 v110, v110
	v_exp_f32_e32 v111, v111
	v_add_f32_e32 v110, 1.0, v110
	v_add_f32_e32 v111, 1.0, v111
	v_rcp_f32_e32 v110, v110
	v_rcp_f32_e32 v111, v111
	s_nop 0
	v_pk_mul_f32 v[94:95], v[94:95], v[110:111]
	s_nop 0
	v_pk_mul_f32 v[94:95], v[90:91], v[94:95]
	v_pk_fma_f32 v[90:91], v[96:97], v[178:179], v[84:85] op_sel_hi:[1,0,1]
	s_nop 0
	v_mul_f32_e32 v96, 0xbfb8aa3b, v90
	v_mul_f32_e32 v97, 0xbfb8aa3b, v91
	v_exp_f32_e32 v96, v96
	v_exp_f32_e32 v97, v97
	v_add_f32_e32 v96, 1.0, v96
	v_add_f32_e32 v97, 1.0, v97
	v_rcp_f32_e32 v96, v96
	v_rcp_f32_e32 v97, v97
	s_nop 0
	v_pk_mul_f32 v[90:91], v[90:91], v[96:97]
	s_nop 0
	v_pk_mul_f32 v[96:97], v[92:93], v[90:91]
	v_cvt_pk_bf16_f32 v92, v94, v95
	v_lshrrev_b32_e32 v94, 8, v185
	v_mad_i32_i24 v94, v94, 44, v161
	v_ashrrev_i32_e32 v95, 31, v94
	v_cvt_pk_bf16_f32 v93, v96, v97
	v_lshlrev_b64 v[94:95], 15, v[94:95]
	v_lshlrev_b32_e32 v96, 7, v185
	v_lshl_add_u64 v[94:95], s[12:13], 0, v[94:95]
	v_and_b32_e32 v96, 0x7f80, v96
	v_mov_b32_e32 v97, v0
	v_lshl_add_u64 v[94:95], v[94:95], 0, v[96:97]
	v_cvt_pk_bf16_f32 v90, v106, v107
	v_cvt_pk_bf16_f32 v91, v108, v109
	v_lshl_add_u64 v[94:95], v[94:95], 0, v[130:131]
	global_store_dwordx4 v[94:95], v[90:93], off sc1
	v_pk_fma_f32 v[78:79], v[78:79], v[176:177], v[98:99] op_sel_hi:[1,0,1]
	v_pk_fma_f32 v[74:75], v[74:75], v[176:177], v[102:103] op_sel_hi:[1,0,1]
	v_mul_f32_e32 v90, 0xbfb8aa3b, v78
	v_mul_f32_e32 v91, 0xbfb8aa3b, v79
	v_exp_f32_e32 v90, v90
	v_exp_f32_e32 v91, v91
	v_pk_fma_f32 v[76:77], v[76:77], v[176:177], v[104:105] op_sel_hi:[1,0,1]
	v_pk_fma_f32 v[70:71], v[70:71], v[176:177], v[82:83] op_sel_hi:[1,0,1]
	v_add_f32_e32 v90, 1.0, v90
	v_add_f32_e32 v91, 1.0, v91
	v_rcp_f32_e32 v90, v90
	v_rcp_f32_e32 v91, v91
	v_pk_fma_f32 v[66:67], v[66:67], v[176:177], v[86:87] op_sel_hi:[1,0,1]
	v_pk_fma_f32 v[68:69], v[68:69], v[176:177], v[88:89] op_sel_hi:[1,0,1]
	v_pk_mul_f32 v[78:79], v[78:79], v[90:91]
	s_nop 0
	v_pk_mul_f32 v[74:75], v[74:75], v[78:79]
	v_pk_fma_f32 v[78:79], v[80:81], v[176:177], v[100:101] op_sel_hi:[1,0,1]
	s_nop 0
	v_mul_f32_e32 v80, 0xbfb8aa3b, v78
	v_mul_f32_e32 v81, 0xbfb8aa3b, v79
	v_exp_f32_e32 v80, v80
	v_exp_f32_e32 v81, v81
	v_add_f32_e32 v80, 1.0, v80
	v_add_f32_e32 v81, 1.0, v81
	v_rcp_f32_e32 v80, v80
	v_rcp_f32_e32 v81, v81
	s_nop 0
	v_pk_mul_f32 v[78:79], v[78:79], v[80:81]
	s_nop 0
	v_pk_mul_f32 v[76:77], v[76:77], v[78:79]
	v_mul_f32_e32 v78, 0xbfb8aa3b, v70
	v_mul_f32_e32 v79, 0xbfb8aa3b, v71
	v_exp_f32_e32 v78, v78
	v_exp_f32_e32 v79, v79
	v_add_f32_e32 v78, 1.0, v78
	v_add_f32_e32 v79, 1.0, v79
	v_rcp_f32_e32 v78, v78
	v_rcp_f32_e32 v79, v79
	s_nop 0
	v_pk_mul_f32 v[70:71], v[70:71], v[78:79]
	s_nop 0
	v_pk_mul_f32 v[70:71], v[66:67], v[70:71]
	v_pk_fma_f32 v[66:67], v[72:73], v[176:177], v[84:85] op_sel_hi:[1,0,1]
	s_nop 0
	v_mul_f32_e32 v72, 0xbfb8aa3b, v66
	v_mul_f32_e32 v73, 0xbfb8aa3b, v67
	v_exp_f32_e32 v72, v72
	v_exp_f32_e32 v73, v73
	v_add_f32_e32 v72, 1.0, v72
	v_add_f32_e32 v73, 1.0, v73
	v_rcp_f32_e32 v72, v72
	v_rcp_f32_e32 v73, v73
	s_nop 0
	v_pk_mul_f32 v[66:67], v[66:67], v[72:73]
	s_nop 0
	v_pk_mul_f32 v[72:73], v[68:69], v[66:67]
	v_cvt_pk_bf16_f32 v68, v70, v71
	v_lshrrev_b32_e32 v70, 8, v183
	v_mad_i32_i24 v70, v70, 44, v161
	v_ashrrev_i32_e32 v71, 31, v70
	v_cvt_pk_bf16_f32 v69, v72, v73
	v_lshlrev_b64 v[70:71], 15, v[70:71]
	v_lshlrev_b32_e32 v72, 7, v183
	v_lshl_add_u64 v[70:71], s[12:13], 0, v[70:71]
	v_and_b32_e32 v72, 0x7f80, v72
	v_mov_b32_e32 v73, v0
	v_lshl_add_u64 v[70:71], v[70:71], 0, v[72:73]
	v_cvt_pk_bf16_f32 v66, v74, v75
	v_cvt_pk_bf16_f32 v67, v76, v77
	v_lshl_add_u64 v[70:71], v[70:71], 0, v[130:131]
	global_store_dwordx4 v[70:71], v[66:69], off sc1
	v_pk_fma_f32 v[62:63], v[62:63], v[174:175], v[98:99] op_sel_hi:[1,0,1]
	v_pk_fma_f32 v[58:59], v[58:59], v[174:175], v[102:103] op_sel_hi:[1,0,1]
	v_mul_f32_e32 v66, 0xbfb8aa3b, v62
	v_mul_f32_e32 v67, 0xbfb8aa3b, v63
	v_exp_f32_e32 v66, v66
	v_exp_f32_e32 v67, v67
	v_pk_fma_f32 v[60:61], v[60:61], v[174:175], v[104:105] op_sel_hi:[1,0,1]
	v_pk_fma_f32 v[54:55], v[54:55], v[174:175], v[82:83] op_sel_hi:[1,0,1]
	v_add_f32_e32 v66, 1.0, v66
	v_add_f32_e32 v67, 1.0, v67
	v_rcp_f32_e32 v66, v66
	v_rcp_f32_e32 v67, v67
	v_pk_fma_f32 v[50:51], v[50:51], v[174:175], v[86:87] op_sel_hi:[1,0,1]
	v_pk_fma_f32 v[52:53], v[52:53], v[174:175], v[88:89] op_sel_hi:[1,0,1]
	v_pk_mul_f32 v[62:63], v[62:63], v[66:67]
	s_nop 0
	v_pk_mul_f32 v[58:59], v[58:59], v[62:63]
	v_pk_fma_f32 v[62:63], v[64:65], v[174:175], v[100:101] op_sel_hi:[1,0,1]
	s_nop 0
	v_mul_f32_e32 v64, 0xbfb8aa3b, v62
	v_mul_f32_e32 v65, 0xbfb8aa3b, v63
	v_exp_f32_e32 v64, v64
	v_exp_f32_e32 v65, v65
	v_add_f32_e32 v64, 1.0, v64
	v_add_f32_e32 v65, 1.0, v65
	v_rcp_f32_e32 v64, v64
	v_rcp_f32_e32 v65, v65
	s_nop 0
	v_pk_mul_f32 v[62:63], v[62:63], v[64:65]
	s_nop 0
	v_pk_mul_f32 v[60:61], v[60:61], v[62:63]
	v_mul_f32_e32 v62, 0xbfb8aa3b, v54
	v_mul_f32_e32 v63, 0xbfb8aa3b, v55
	v_exp_f32_e32 v62, v62
	v_exp_f32_e32 v63, v63
	v_add_f32_e32 v62, 1.0, v62
	v_add_f32_e32 v63, 1.0, v63
	v_rcp_f32_e32 v62, v62
	v_rcp_f32_e32 v63, v63
	s_nop 0
	v_pk_mul_f32 v[54:55], v[54:55], v[62:63]
	s_nop 0
	v_pk_mul_f32 v[54:55], v[50:51], v[54:55]
	v_pk_fma_f32 v[50:51], v[56:57], v[174:175], v[84:85] op_sel_hi:[1,0,1]
	s_nop 0
	v_mul_f32_e32 v56, 0xbfb8aa3b, v50
	v_mul_f32_e32 v57, 0xbfb8aa3b, v51
	v_exp_f32_e32 v56, v56
	v_exp_f32_e32 v57, v57
	v_add_f32_e32 v56, 1.0, v56
	v_add_f32_e32 v57, 1.0, v57
	v_rcp_f32_e32 v56, v56
	v_rcp_f32_e32 v57, v57
	s_nop 0
	v_pk_mul_f32 v[50:51], v[50:51], v[56:57]
	s_nop 0
	v_pk_mul_f32 v[56:57], v[52:53], v[50:51]
	v_cvt_pk_bf16_f32 v52, v54, v55
	v_lshrrev_b32_e32 v54, 8, v181
	v_mad_i32_i24 v54, v54, 44, v161
	v_ashrrev_i32_e32 v55, 31, v54
	v_cvt_pk_bf16_f32 v53, v56, v57
	v_lshlrev_b64 v[54:55], 15, v[54:55]
	v_lshlrev_b32_e32 v56, 7, v181
	v_lshl_add_u64 v[54:55], s[12:13], 0, v[54:55]
	v_and_b32_e32 v56, 0x7f80, v56
	v_mov_b32_e32 v57, v0
	v_lshl_add_u64 v[54:55], v[54:55], 0, v[56:57]
	v_cvt_pk_bf16_f32 v50, v58, v59
	v_cvt_pk_bf16_f32 v51, v60, v61
	v_lshl_add_u64 v[54:55], v[54:55], 0, v[130:131]
	global_store_dwordx4 v[54:55], v[50:53], off sc1
	v_pk_fma_f32 v[46:47], v[46:47], v[172:173], v[98:99] op_sel_hi:[1,0,1]
	v_pk_fma_f32 v[42:43], v[42:43], v[172:173], v[102:103] op_sel_hi:[1,0,1]
	v_mul_f32_e32 v50, 0xbfb8aa3b, v46
	v_mul_f32_e32 v51, 0xbfb8aa3b, v47
	v_exp_f32_e32 v50, v50
	v_exp_f32_e32 v51, v51
	v_pk_fma_f32 v[44:45], v[44:45], v[172:173], v[104:105] op_sel_hi:[1,0,1]
	v_pk_fma_f32 v[38:39], v[38:39], v[172:173], v[82:83] op_sel_hi:[1,0,1]
	v_add_f32_e32 v50, 1.0, v50
	v_add_f32_e32 v51, 1.0, v51
	v_rcp_f32_e32 v50, v50
	v_rcp_f32_e32 v51, v51
	v_pk_fma_f32 v[34:35], v[34:35], v[172:173], v[86:87] op_sel_hi:[1,0,1]
	v_pk_fma_f32 v[36:37], v[36:37], v[172:173], v[88:89] op_sel_hi:[1,0,1]
	v_pk_mul_f32 v[46:47], v[46:47], v[50:51]
	s_nop 0
	v_pk_mul_f32 v[42:43], v[42:43], v[46:47]
	v_pk_fma_f32 v[46:47], v[48:49], v[172:173], v[100:101] op_sel_hi:[1,0,1]
	s_nop 0
	v_mul_f32_e32 v48, 0xbfb8aa3b, v46
	v_mul_f32_e32 v49, 0xbfb8aa3b, v47
	v_exp_f32_e32 v48, v48
	v_exp_f32_e32 v49, v49
	v_add_f32_e32 v48, 1.0, v48
	v_add_f32_e32 v49, 1.0, v49
	v_rcp_f32_e32 v48, v48
	v_rcp_f32_e32 v49, v49
	s_nop 0
	v_pk_mul_f32 v[46:47], v[46:47], v[48:49]
	s_nop 0
	v_pk_mul_f32 v[44:45], v[44:45], v[46:47]
	v_mul_f32_e32 v46, 0xbfb8aa3b, v38
	v_mul_f32_e32 v47, 0xbfb8aa3b, v39
	v_exp_f32_e32 v46, v46
	v_exp_f32_e32 v47, v47
	v_add_f32_e32 v46, 1.0, v46
	v_add_f32_e32 v47, 1.0, v47
	v_rcp_f32_e32 v46, v46
	v_rcp_f32_e32 v47, v47
	s_nop 0
	v_pk_mul_f32 v[38:39], v[38:39], v[46:47]
	s_nop 0
	v_pk_mul_f32 v[38:39], v[34:35], v[38:39]
	v_pk_fma_f32 v[34:35], v[40:41], v[172:173], v[84:85] op_sel_hi:[1,0,1]
	s_nop 0
	v_mul_f32_e32 v40, 0xbfb8aa3b, v34
	v_mul_f32_e32 v41, 0xbfb8aa3b, v35
	v_exp_f32_e32 v40, v40
	v_exp_f32_e32 v41, v41
	v_add_f32_e32 v40, 1.0, v40
	v_add_f32_e32 v41, 1.0, v41
	v_rcp_f32_e32 v40, v40
	v_rcp_f32_e32 v41, v41
	s_nop 0
	v_pk_mul_f32 v[34:35], v[34:35], v[40:41]
	s_nop 0
	v_pk_mul_f32 v[40:41], v[36:37], v[34:35]
	v_cvt_pk_bf16_f32 v36, v38, v39
	v_lshrrev_b32_e32 v38, 8, v179
	v_mad_i32_i24 v38, v38, 44, v161
	v_ashrrev_i32_e32 v39, 31, v38
	v_cvt_pk_bf16_f32 v37, v40, v41
	v_lshlrev_b64 v[38:39], 15, v[38:39]
	v_lshlrev_b32_e32 v40, 7, v179
	v_lshl_add_u64 v[38:39], s[12:13], 0, v[38:39]
	v_and_b32_e32 v40, 0x7f80, v40
	v_mov_b32_e32 v41, v0
	v_lshl_add_u64 v[38:39], v[38:39], 0, v[40:41]
	v_cvt_pk_bf16_f32 v34, v42, v43
	v_cvt_pk_bf16_f32 v35, v44, v45
	v_lshl_add_u64 v[38:39], v[38:39], 0, v[130:131]
	global_store_dwordx4 v[38:39], v[34:37], off sc1
	v_pk_fma_f32 v[30:31], v[30:31], v[158:159], v[98:99] op_sel_hi:[1,0,1]
	v_pk_fma_f32 v[26:27], v[26:27], v[158:159], v[102:103] op_sel_hi:[1,0,1]
	v_mul_f32_e32 v34, 0xbfb8aa3b, v30
	v_mul_f32_e32 v35, 0xbfb8aa3b, v31
	v_exp_f32_e32 v34, v34
	v_exp_f32_e32 v35, v35
	v_pk_fma_f32 v[28:29], v[28:29], v[158:159], v[104:105] op_sel_hi:[1,0,1]
	v_pk_fma_f32 v[22:23], v[22:23], v[158:159], v[82:83] op_sel_hi:[1,0,1]
	v_add_f32_e32 v34, 1.0, v34
	v_add_f32_e32 v35, 1.0, v35
	v_rcp_f32_e32 v34, v34
	v_rcp_f32_e32 v35, v35
	v_pk_fma_f32 v[18:19], v[18:19], v[158:159], v[86:87] op_sel_hi:[1,0,1]
	v_pk_fma_f32 v[20:21], v[20:21], v[158:159], v[88:89] op_sel_hi:[1,0,1]
	v_pk_mul_f32 v[30:31], v[30:31], v[34:35]
	s_nop 0
	v_pk_mul_f32 v[26:27], v[26:27], v[30:31]
	v_pk_fma_f32 v[30:31], v[32:33], v[158:159], v[100:101] op_sel_hi:[1,0,1]
	s_nop 0
	v_mul_f32_e32 v32, 0xbfb8aa3b, v30
	v_mul_f32_e32 v33, 0xbfb8aa3b, v31
	v_exp_f32_e32 v32, v32
	v_exp_f32_e32 v33, v33
	v_add_f32_e32 v32, 1.0, v32
	v_add_f32_e32 v33, 1.0, v33
	v_rcp_f32_e32 v32, v32
	v_rcp_f32_e32 v33, v33
	s_nop 0
	v_pk_mul_f32 v[30:31], v[30:31], v[32:33]
	s_nop 0
	v_pk_mul_f32 v[28:29], v[28:29], v[30:31]
	v_mul_f32_e32 v30, 0xbfb8aa3b, v22
	v_mul_f32_e32 v31, 0xbfb8aa3b, v23
	v_exp_f32_e32 v30, v30
	v_exp_f32_e32 v31, v31
	v_add_f32_e32 v30, 1.0, v30
	v_add_f32_e32 v31, 1.0, v31
	v_rcp_f32_e32 v30, v30
	v_rcp_f32_e32 v31, v31
	s_nop 0
	v_pk_mul_f32 v[22:23], v[22:23], v[30:31]
	s_nop 0
	v_pk_mul_f32 v[22:23], v[18:19], v[22:23]
	v_pk_fma_f32 v[18:19], v[24:25], v[158:159], v[84:85] op_sel_hi:[1,0,1]
	s_nop 0
	v_mul_f32_e32 v24, 0xbfb8aa3b, v18
	v_mul_f32_e32 v25, 0xbfb8aa3b, v19
	v_exp_f32_e32 v24, v24
	v_exp_f32_e32 v25, v25
	v_add_f32_e32 v24, 1.0, v24
	v_add_f32_e32 v25, 1.0, v25
	v_rcp_f32_e32 v24, v24
	v_rcp_f32_e32 v25, v25
	s_nop 0
	v_pk_mul_f32 v[18:19], v[18:19], v[24:25]
	s_nop 0
	v_pk_mul_f32 v[24:25], v[20:21], v[18:19]
	v_cvt_pk_bf16_f32 v20, v22, v23
	v_lshrrev_b32_e32 v22, 8, v177
	v_mad_i32_i24 v22, v22, 44, v161
	v_ashrrev_i32_e32 v23, 31, v22
	v_cvt_pk_bf16_f32 v21, v24, v25
	v_lshlrev_b64 v[22:23], 15, v[22:23]
	v_lshlrev_b32_e32 v24, 7, v177
	v_lshl_add_u64 v[22:23], s[12:13], 0, v[22:23]
	v_and_b32_e32 v24, 0x7f80, v24
	v_mov_b32_e32 v25, v0
	v_lshl_add_u64 v[22:23], v[22:23], 0, v[24:25]
	v_cvt_pk_bf16_f32 v18, v26, v27
	v_cvt_pk_bf16_f32 v19, v28, v29
	v_lshl_add_u64 v[22:23], v[22:23], 0, v[130:131]
	global_store_dwordx4 v[22:23], v[18:21], off sc1
	v_pk_fma_f32 v[14:15], v[14:15], v[160:161], v[98:99] op_sel_hi:[1,0,1]
	v_pk_fma_f32 v[10:11], v[10:11], v[160:161], v[102:103] op_sel_hi:[1,0,1]
	v_mul_f32_e32 v18, 0xbfb8aa3b, v14
	v_mul_f32_e32 v19, 0xbfb8aa3b, v15
	v_exp_f32_e32 v18, v18
	v_exp_f32_e32 v19, v19
	v_pk_fma_f32 v[12:13], v[12:13], v[160:161], v[104:105] op_sel_hi:[1,0,1]
	v_pk_fma_f32 v[6:7], v[6:7], v[160:161], v[82:83] op_sel_hi:[1,0,1]
	v_add_f32_e32 v18, 1.0, v18
	v_add_f32_e32 v19, 1.0, v19
	v_rcp_f32_e32 v18, v18
	v_rcp_f32_e32 v19, v19
	v_pk_fma_f32 v[2:3], v[2:3], v[160:161], v[86:87] op_sel_hi:[1,0,1]
	v_pk_fma_f32 v[4:5], v[4:5], v[160:161], v[88:89] op_sel_hi:[1,0,1]
	s_and_b64 vcc, exec, s[36:37]
	v_pk_mul_f32 v[14:15], v[14:15], v[18:19]
	s_mov_b32 s38, s2
	v_pk_mul_f32 v[10:11], v[10:11], v[14:15]
	v_pk_fma_f32 v[14:15], v[16:17], v[160:161], v[100:101] op_sel_hi:[1,0,1]
	s_mov_b32 s10, s4
	v_mul_f32_e32 v16, 0xbfb8aa3b, v14
	v_mul_f32_e32 v17, 0xbfb8aa3b, v15
	v_exp_f32_e32 v16, v16
	v_exp_f32_e32 v17, v17
	s_mov_b64 s[14:15], s[8:9]
	v_add_f32_e32 v16, 1.0, v16
	v_add_f32_e32 v17, 1.0, v17
	v_rcp_f32_e32 v16, v16
	v_rcp_f32_e32 v17, v17
	s_nop 0
	v_pk_mul_f32 v[14:15], v[14:15], v[16:17]
	s_nop 0
	v_pk_mul_f32 v[12:13], v[12:13], v[14:15]
	v_mul_f32_e32 v14, 0xbfb8aa3b, v6
	v_mul_f32_e32 v15, 0xbfb8aa3b, v7
	v_exp_f32_e32 v14, v14
	v_exp_f32_e32 v15, v15
	v_add_f32_e32 v14, 1.0, v14
	v_add_f32_e32 v15, 1.0, v15
	v_rcp_f32_e32 v14, v14
	v_rcp_f32_e32 v15, v15
	s_nop 0
	v_pk_mul_f32 v[6:7], v[6:7], v[14:15]
	s_nop 0
	v_pk_mul_f32 v[6:7], v[2:3], v[6:7]
	v_pk_fma_f32 v[2:3], v[8:9], v[160:161], v[84:85] op_sel_hi:[1,0,1]
	s_nop 0
	v_mul_f32_e32 v8, 0xbfb8aa3b, v2
	v_mul_f32_e32 v9, 0xbfb8aa3b, v3
	v_exp_f32_e32 v8, v8
	v_exp_f32_e32 v9, v9
	v_add_f32_e32 v8, 1.0, v8
	v_add_f32_e32 v9, 1.0, v9
	v_rcp_f32_e32 v8, v8
	v_rcp_f32_e32 v9, v9
	s_nop 0
	v_pk_mul_f32 v[2:3], v[2:3], v[8:9]
	s_nop 0
	v_pk_mul_f32 v[8:9], v[4:5], v[2:3]
	v_cvt_pk_bf16_f32 v4, v6, v7
	v_lshrrev_b32_e32 v6, 8, v175
	v_mad_i32_i24 v6, v6, 44, v161
	v_ashrrev_i32_e32 v7, 31, v6
	v_cvt_pk_bf16_f32 v5, v8, v9
	v_lshlrev_b64 v[6:7], 15, v[6:7]
	v_lshlrev_b32_e32 v8, 7, v175
	v_lshl_add_u64 v[6:7], s[12:13], 0, v[6:7]
	v_and_b32_e32 v8, 0x7f80, v8
	v_mov_b32_e32 v9, v0
	v_lshl_add_u64 v[6:7], v[6:7], 0, v[8:9]
	v_cvt_pk_bf16_f32 v2, v10, v11
	v_cvt_pk_bf16_f32 v3, v12, v13
	v_lshl_add_u64 v[6:7], v[6:7], 0, v[130:131]
	s_mov_b64 s[12:13], s[6:7]
	global_store_dwordx4 v[6:7], v[2:5], off sc1
	s_cbranch_vccnz .LBB0_875
